# big-GEMM K-loops: loop counter / pointer bumps / exit compare moved in front of the loop-back barrier (only the branch stays after it)
# speedup vs baseline: 1.0012x; 1.0012x over previous
; #define PG8_STAGE(bufoff, gbase, voff) do { _Pragma("unroll") for (int _i = 0; _i < 2; ++_i) \
;         __builtin_amdgcn_global_load_lds((const unsigned*)((const char*)(gbase) + (voff)[_i]), (PG8_LAS unsigned*)(lds + (bufoff) + ldsw + _i * 8192), 16, 0, 0); } while (0)
; #define PG8_LDA(dst, b, h) do { _Pragma("unroll") for (int m = 0; m < 4; ++m) _Pragma("unroll") for (int k = 0; k < 2; ++k) dst[m][k] = *(const PG8_LAS bf16x8*)(lds + PG8_SA(b, h) + aoff + m * 2048 + k * 1024); } while (0)
; #define PG8_LDB(dst, b, h) do { _Pragma("unroll") for (int n = 0; n < 2; ++n) _Pragma("unroll") for (int k = 0; k < 2; ++k) dst[n][k] = *(const PG8_LAS bf16x8*)(lds + PG8_SB(b, h) + boff + n * 2048 + k * 1024); } while (0)
; #define PG8_MMA(ai, bj, At, Bt) do { __builtin_amdgcn_s_setprio(1); _Pragma("unroll") for (int m = 0; m < 4; ++m) _Pragma("unroll") for (int n = 0; n < 2; ++n) _Pragma("unroll") for (int k = 0; k < 2; ++k) \
;         acc[ai][bj][m][n] = __builtin_amdgcn_mfma_f32_16x16x32_bf16(Bt[n][k], At[m][k], acc[ai][bj][m][n], 0, 0, 0); __builtin_amdgcn_s_setprio(0); } while (0)
; #define PG8_WAIT_V(n) asm volatile("s_waitcnt vmcnt(" #n ")" ::: "memory")
; #define PG8_BAR __builtin_amdgcn_s_barrier()
; template <class Epi, class Sched, bool ALIGN_EPI = false, bool SP2 = false>
; __device__ __forceinline__ void gemm_phase(PG8_LAS unsigned char* lds, const Gemm g, const Sched& S, const Epi& E) {
;     ...
;         for (int t = 0; t < nt; t += 2) {
;             const bool last = (t == nt - 2);
;             const char* a1 = cA + (size_t)(t + 1) * kstep;
;             const char* a2 = last ? nA : cA + (size_t)(t + 2) * kstep; const char* b2 = last ? nB : cB + (size_t)(t + 2) * kstep;
;             const char* a3 = a2 + kstep; const char* b3 = b2 + kstep;
;             if (last && has_next) S.a_ready(nxt);
;             if constexpr (SP2) {
;             PG8_LDB(B0, 0, 0); PG8_LDB(B1, 0, 1); PG8_SCHED; PG8_LDA(At, 0, 0); PG8_STAGE(PG8_SA(1, 1), a1 + hstep, voffA);
;             PG8_WAIT_V(8); PG8_WAIT_L(0); PG8_BAR; PG8_MMA(0, 0, At, B0); PG8_MMA(0, 1, At, B1); PG8_BAR; PG8_SCHED;
;             PG8_LDA(At, 0, 1); PG8_STAGE(PG8_SB(0, 0), b2, voffB); PG8_STAGE(PG8_SB(0, 1), b2 + hstep, voffB); PG8_STAGE(PG8_SA(0, 0), a2, voffA);
;             PG8_WAIT_V(8); PG8_WAIT_L(0); PG8_BAR; PG8_MMA(1, 0, At, B0); PG8_MMA(1, 1, At, B1); PG8_BAR; PG8_SCHED;
.LBB0_253:
	ds_read_b128 v[148:151], v161
	ds_read_b128 v[166:169], v161 offset:1024
	ds_read_b128 v[170:173], v161 offset:2048
	ds_read_b128 v[174:177], v161 offset:3072
	ds_read_b128 v[178:181], v162
	ds_read_b128 v[184:187], v162 offset:1024
	ds_read_b128 v[188:191], v162 offset:2048
	ds_read_b128 v[192:195], v162 offset:3072
	s_add_u32 s30, s28, 0xfff80080
	s_addc_u32 s31, s29, -1
	s_cmp_eq_u32 s56, 28
	s_cselect_b32 s35, s3, s31
	s_cselect_b32 s34, s21, s30
	s_cselect_b32 s31, s19, s55
	s_cselect_b32 s30, s27, s54
	v_lshl_add_u64 v[152:153], s[28:29], 0, v[140:141]
	s_add_i32 m0, s38, 0xc000
	ds_read_b128 v[196:199], v163
	ds_read_b128 v[200:203], v163 offset:1024
	ds_read_b128 v[204:207], v163 offset:2048
	ds_read_b128 v[208:211], v163 offset:3072
	ds_read_b128 v[212:215], v163 offset:4096
	ds_read_b128 v[216:219], v163 offset:5120
	ds_read_b128 v[220:223], v163 offset:6144
	ds_read_b128 v[224:227], v163 offset:7168
	global_load_lds_dwordx4 v[152:153], off
	v_lshl_add_u64 v[152:153], s[28:29], 0, v[142:143]
	s_add_i32 m0, s38, 0xe000
	s_nop 0
	global_load_lds_dwordx4 v[152:153], off
	s_waitcnt vmcnt(8)
	s_waitcnt lgkmcnt(0)
	s_barrier
	s_setprio 1
	s_waitcnt lgkmcnt(0)
	v_mfma_f32_16x16x32_bf16 v[124:127], v[148:151], v[196:199], v[124:127]
	v_mfma_f32_16x16x32_bf16 v[120:123], v[170:173], v[196:199], v[120:123]
	v_mfma_f32_16x16x32_bf16 v[116:119], v[148:151], v[204:207], v[116:119]
	v_mfma_f32_16x16x32_bf16 v[112:115], v[170:173], v[204:207], v[112:115]
	v_mfma_f32_16x16x32_bf16 v[108:111], v[148:151], v[212:215], v[108:111]
	v_mfma_f32_16x16x32_bf16 v[104:107], v[170:173], v[212:215], v[104:107]
	v_mfma_f32_16x16x32_bf16 v[100:103], v[148:151], v[220:223], v[100:103]
	v_mfma_f32_16x16x32_bf16 v[96:99], v[170:173], v[220:223], v[96:99]
	v_mfma_f32_16x16x32_bf16 v[124:127], v[166:169], v[200:203], v[124:127]
	v_mfma_f32_16x16x32_bf16 v[120:123], v[174:177], v[200:203], v[120:123]
	v_mfma_f32_16x16x32_bf16 v[116:119], v[166:169], v[208:211], v[116:119]
	v_mfma_f32_16x16x32_bf16 v[112:115], v[174:177], v[208:211], v[112:115]
	v_mfma_f32_16x16x32_bf16 v[108:111], v[166:169], v[216:219], v[108:111]
	v_mfma_f32_16x16x32_bf16 v[104:107], v[174:177], v[216:219], v[104:107]
	v_mfma_f32_16x16x32_bf16 v[100:103], v[166:169], v[224:227], v[100:103]
	v_mfma_f32_16x16x32_bf16 v[96:99], v[174:177], v[224:227], v[96:99]
	s_setprio 0
	s_setprio 1
	v_mfma_f32_16x16x32_bf16 v[92:95], v[178:181], v[196:199], v[92:95]
	v_mfma_f32_16x16x32_bf16 v[88:91], v[188:191], v[196:199], v[88:91]
	v_mfma_f32_16x16x32_bf16 v[84:87], v[178:181], v[204:207], v[84:87]
	v_mfma_f32_16x16x32_bf16 v[80:83], v[188:191], v[204:207], v[80:83]
	v_mfma_f32_16x16x32_bf16 v[76:79], v[178:181], v[212:215], v[76:79]
	v_mfma_f32_16x16x32_bf16 v[72:75], v[188:191], v[212:215], v[72:75]
	v_mfma_f32_16x16x32_bf16 v[68:71], v[178:181], v[220:223], v[68:71]
	v_mfma_f32_16x16x32_bf16 v[64:67], v[188:191], v[220:223], v[64:67]
	v_mfma_f32_16x16x32_bf16 v[92:95], v[184:187], v[200:203], v[92:95]
	v_mfma_f32_16x16x32_bf16 v[88:91], v[192:195], v[200:203], v[88:91]
	v_mfma_f32_16x16x32_bf16 v[84:87], v[184:187], v[208:211], v[84:87]
	v_mfma_f32_16x16x32_bf16 v[80:83], v[192:195], v[208:211], v[80:83]
	v_mfma_f32_16x16x32_bf16 v[76:79], v[184:187], v[216:219], v[76:79]
	v_mfma_f32_16x16x32_bf16 v[72:75], v[192:195], v[216:219], v[72:75]
	v_mfma_f32_16x16x32_bf16 v[68:71], v[184:187], v[224:227], v[68:71]
	v_mfma_f32_16x16x32_bf16 v[64:67], v[192:195], v[224:227], v[64:67]
	s_setprio 0
	s_barrier
	s_add_i32 s57, s48, s37
	v_lshl_add_u64 v[152:153], s[30:31], 0, v[130:131]
	s_mov_b32 m0, s57
	ds_read_b128 v[196:199], v163 offset:16384
	ds_read_b128 v[200:203], v163 offset:17408
	ds_read_b128 v[204:207], v163 offset:18432
	ds_read_b128 v[208:211], v163 offset:19456
	ds_read_b128 v[212:215], v163 offset:20480
	ds_read_b128 v[216:219], v163 offset:21504
	ds_read_b128 v[220:223], v163 offset:22528
	ds_read_b128 v[224:227], v163 offset:23552
	global_load_lds_dwordx4 v[152:153], off
	s_add_i32 m0, s57, 0x2000
	s_add_u32 s58, s30, 0x80000
	v_lshl_add_u64 v[228:229], s[30:31], 0, v[134:135]
	s_addc_u32 s59, s31, 0
	s_add_i32 s57, s49, s37
	global_load_lds_dwordx4 v[228:229], off
	v_lshl_add_u64 v[230:231], s[58:59], 0, v[130:131]
	s_mov_b32 m0, s57
	v_lshl_add_u64 v[232:233], s[34:35], 0, v[132:133]
	global_load_lds_dwordx4 v[230:231], off
	v_lshl_add_u64 v[230:231], s[58:59], 0, v[134:135]
	s_add_i32 m0, s57, 0x2000
	s_nop 0
	global_load_lds_dwordx4 v[230:231], off
	v_lshl_add_u64 v[230:231], s[34:35], 0, v[128:129]
	s_mov_b32 m0, s38
	s_nop 0
	global_load_lds_dwordx4 v[230:231], off
	s_mov_b32 m0, s39
	s_nop 0
	global_load_lds_dwordx4 v[232:233], off
	s_waitcnt vmcnt(8)
	s_waitcnt lgkmcnt(0)
	s_barrier
; #define PG8_STAGE(bufoff, gbase, voff) do { _Pragma("unroll") for (int _i = 0; _i < 2; ++_i) \
;         __builtin_amdgcn_global_load_lds((const unsigned*)((const char*)(gbase) + (voff)[_i]), (PG8_LAS unsigned*)(lds + (bufoff) + ldsw + _i * 8192), 16, 0, 0); } while (0)
; #define PG8_LDA(dst, b, h) do { _Pragma("unroll") for (int m = 0; m < 4; ++m) _Pragma("unroll") for (int k = 0; k < 2; ++k) dst[m][k] = *(const PG8_LAS bf16x8*)(lds + PG8_SA(b, h) + aoff + m * 2048 + k * 1024); } while (0)
; #define PG8_LDB(dst, b, h) do { _Pragma("unroll") for (int n = 0; n < 2; ++n) _Pragma("unroll") for (int k = 0; k < 2; ++k) dst[n][k] = *(const PG8_LAS bf16x8*)(lds + PG8_SB(b, h) + boff + n * 2048 + k * 1024); } while (0)
; #define PG8_MMA(ai, bj, At, Bt) do { __builtin_amdgcn_s_setprio(1); _Pragma("unroll") for (int m = 0; m < 4; ++m) _Pragma("unroll") for (int n = 0; n < 2; ++n) _Pragma("unroll") for (int k = 0; k < 2; ++k) \
;         acc[ai][bj][m][n] = __builtin_amdgcn_mfma_f32_16x16x32_bf16(Bt[n][k], At[m][k], acc[ai][bj][m][n], 0, 0, 0); __builtin_amdgcn_s_setprio(0); } while (0)
; #define PG8_WAIT_V(n) asm volatile("s_waitcnt vmcnt(" #n ")" ::: "memory")
; #define PG8_WAIT_L(n) asm volatile("s_waitcnt lgkmcnt(" #n ")" ::: "memory")
; #define PG8_BAR __builtin_amdgcn_s_barrier()
; #define PG8_SCHED __builtin_amdgcn_sched_barrier(0)
; template <class Epi, class Sched, bool ALIGN_EPI = false, bool SP2 = false>
; __device__ __forceinline__ void gemm_phase(PG8_LAS unsigned char* lds, const Gemm g, const Sched& S, const Epi& E) {
;     ...
;             PG8_WAIT_V(8); PG8_WAIT_L(0); PG8_BAR; PG8_MMA(1, 0, At, B0); PG8_MMA(1, 1, At, B1); PG8_BAR; PG8_SCHED;
;             PG8_LDB(B0, 1, 0); PG8_LDB(B1, 1, 1); PG8_SCHED; PG8_LDA(At, 1, 0); PG8_STAGE(PG8_SA(0, 1), a2 + hstep, voffA);
;             PG8_WAIT_V(8); PG8_WAIT_L(0); PG8_BAR; PG8_MMA(0, 0, At, B0); PG8_MMA(0, 1, At, B1); PG8_BAR; PG8_SCHED;
	s_setprio 1
	s_waitcnt lgkmcnt(0)
	v_mfma_f32_16x16x32_bf16 v[60:63], v[148:151], v[196:199], v[60:63]
	v_mfma_f32_16x16x32_bf16 v[56:59], v[170:173], v[196:199], v[56:59]
	v_mfma_f32_16x16x32_bf16 v[52:55], v[148:151], v[204:207], v[52:55]
	v_mfma_f32_16x16x32_bf16 v[48:51], v[170:173], v[204:207], v[48:51]
	v_mfma_f32_16x16x32_bf16 v[44:47], v[148:151], v[212:215], v[44:47]
	v_mfma_f32_16x16x32_bf16 v[40:43], v[170:173], v[212:215], v[40:43]
	v_mfma_f32_16x16x32_bf16 v[36:39], v[148:151], v[220:223], v[36:39]
	v_mfma_f32_16x16x32_bf16 v[32:35], v[170:173], v[220:223], v[32:35]
	v_mfma_f32_16x16x32_bf16 v[60:63], v[166:169], v[200:203], v[60:63]
	v_mfma_f32_16x16x32_bf16 v[56:59], v[174:177], v[200:203], v[56:59]
	v_mfma_f32_16x16x32_bf16 v[52:55], v[166:169], v[208:211], v[52:55]
	v_mfma_f32_16x16x32_bf16 v[48:51], v[174:177], v[208:211], v[48:51]
	v_mfma_f32_16x16x32_bf16 v[44:47], v[166:169], v[216:219], v[44:47]
	v_mfma_f32_16x16x32_bf16 v[40:43], v[174:177], v[216:219], v[40:43]
	v_mfma_f32_16x16x32_bf16 v[36:39], v[166:169], v[224:227], v[36:39]
	v_mfma_f32_16x16x32_bf16 v[32:35], v[174:177], v[224:227], v[32:35]
	s_setprio 0
	s_setprio 1
	v_mfma_f32_16x16x32_bf16 v[28:31], v[178:181], v[196:199], v[28:31]
	v_mfma_f32_16x16x32_bf16 v[24:27], v[188:191], v[196:199], v[24:27]
	v_mfma_f32_16x16x32_bf16 v[20:23], v[178:181], v[204:207], v[20:23]
	v_mfma_f32_16x16x32_bf16 v[16:19], v[188:191], v[204:207], v[16:19]
	v_mfma_f32_16x16x32_bf16 v[12:15], v[178:181], v[212:215], v[12:15]
	v_mfma_f32_16x16x32_bf16 v[8:11], v[188:191], v[212:215], v[8:11]
	v_mfma_f32_16x16x32_bf16 v[4:7], v[178:181], v[220:223], v[4:7]
	v_mfma_f32_16x16x32_bf16 v[0:3], v[188:191], v[220:223], v[0:3]
	v_mfma_f32_16x16x32_bf16 v[28:31], v[184:187], v[200:203], v[28:31]
	v_mfma_f32_16x16x32_bf16 v[24:27], v[192:195], v[200:203], v[24:27]
	v_mfma_f32_16x16x32_bf16 v[20:23], v[184:187], v[208:211], v[20:23]
	v_mfma_f32_16x16x32_bf16 v[16:19], v[192:195], v[208:211], v[16:19]
	v_mfma_f32_16x16x32_bf16 v[12:15], v[184:187], v[216:219], v[12:15]
	v_mfma_f32_16x16x32_bf16 v[8:11], v[192:195], v[216:219], v[8:11]
	v_mfma_f32_16x16x32_bf16 v[4:7], v[184:187], v[224:227], v[4:7]
	v_mfma_f32_16x16x32_bf16 v[0:3], v[192:195], v[224:227], v[0:3]
	s_setprio 0
	s_barrier
	s_add_i32 s57, 0, 0x18000
	v_add_u32_e32 v136, s57, v159
	s_add_i32 s58, 0, 0x1c000
	ds_read_b128 v[148:151], v136
	ds_read_b128 v[166:169], v136 offset:1024
	ds_read_b128 v[170:173], v136 offset:2048
	ds_read_b128 v[174:177], v136 offset:3072
	v_add_u32_e32 v136, s58, v159
	ds_read_b128 v[178:181], v136
	ds_read_b128 v[184:187], v136 offset:1024
	ds_read_b128 v[188:191], v136 offset:2048
	ds_read_b128 v[192:195], v136 offset:3072
	s_add_u32 s34, s34, 0x80000
	s_addc_u32 s35, s35, 0
	s_mov_b32 m0, s40
	v_lshl_add_u64 v[234:235], s[34:35], 0, v[128:129]
	ds_read_b128 v[196:199], v163 offset:32768
	ds_read_b128 v[200:203], v163 offset:33792
	ds_read_b128 v[204:207], v163 offset:34816
	ds_read_b128 v[208:211], v163 offset:35840
	ds_read_b128 v[212:215], v163 offset:36864
	ds_read_b128 v[216:219], v163 offset:37888
	ds_read_b128 v[220:223], v163 offset:38912
	ds_read_b128 v[224:227], v163 offset:39936
	global_load_lds_dwordx4 v[234:235], off
	v_lshl_add_u64 v[234:235], s[34:35], 0, v[132:133]
	s_mov_b32 m0, s41
	s_nop 0
	global_load_lds_dwordx4 v[234:235], off
	s_waitcnt vmcnt(8)
	s_waitcnt lgkmcnt(0)
	s_barrier
	s_setprio 1
	s_waitcnt lgkmcnt(0)
	v_mfma_f32_16x16x32_bf16 v[124:127], v[148:151], v[196:199], v[124:127]
	v_mfma_f32_16x16x32_bf16 v[120:123], v[170:173], v[196:199], v[120:123]
	v_mfma_f32_16x16x32_bf16 v[116:119], v[148:151], v[204:207], v[116:119]
	v_mfma_f32_16x16x32_bf16 v[112:115], v[170:173], v[204:207], v[112:115]
	v_mfma_f32_16x16x32_bf16 v[108:111], v[148:151], v[212:215], v[108:111]
	v_mfma_f32_16x16x32_bf16 v[104:107], v[170:173], v[212:215], v[104:107]
	v_mfma_f32_16x16x32_bf16 v[100:103], v[148:151], v[220:223], v[100:103]
	v_mfma_f32_16x16x32_bf16 v[96:99], v[170:173], v[220:223], v[96:99]
	v_mfma_f32_16x16x32_bf16 v[124:127], v[166:169], v[200:203], v[124:127]
	v_mfma_f32_16x16x32_bf16 v[120:123], v[174:177], v[200:203], v[120:123]
	v_mfma_f32_16x16x32_bf16 v[116:119], v[166:169], v[208:211], v[116:119]
	v_mfma_f32_16x16x32_bf16 v[112:115], v[174:177], v[208:211], v[112:115]
	v_mfma_f32_16x16x32_bf16 v[108:111], v[166:169], v[216:219], v[108:111]
	v_mfma_f32_16x16x32_bf16 v[104:107], v[174:177], v[216:219], v[104:107]
	v_mfma_f32_16x16x32_bf16 v[100:103], v[166:169], v[224:227], v[100:103]
	v_mfma_f32_16x16x32_bf16 v[96:99], v[174:177], v[224:227], v[96:99]
	s_setprio 0
	s_setprio 1
	v_mfma_f32_16x16x32_bf16 v[92:95], v[178:181], v[196:199], v[92:95]
	v_mfma_f32_16x16x32_bf16 v[88:91], v[188:191], v[196:199], v[88:91]
	v_mfma_f32_16x16x32_bf16 v[84:87], v[178:181], v[204:207], v[84:87]
	v_mfma_f32_16x16x32_bf16 v[80:83], v[188:191], v[204:207], v[80:83]
	v_mfma_f32_16x16x32_bf16 v[76:79], v[178:181], v[212:215], v[76:79]
	v_mfma_f32_16x16x32_bf16 v[72:75], v[188:191], v[212:215], v[72:75]
	v_mfma_f32_16x16x32_bf16 v[68:71], v[178:181], v[220:223], v[68:71]
	v_mfma_f32_16x16x32_bf16 v[64:67], v[188:191], v[220:223], v[64:67]
	v_mfma_f32_16x16x32_bf16 v[92:95], v[184:187], v[200:203], v[92:95]
	v_mfma_f32_16x16x32_bf16 v[88:91], v[192:195], v[200:203], v[88:91]
	v_mfma_f32_16x16x32_bf16 v[84:87], v[184:187], v[208:211], v[84:87]
	v_mfma_f32_16x16x32_bf16 v[80:83], v[192:195], v[208:211], v[80:83]
	v_mfma_f32_16x16x32_bf16 v[76:79], v[184:187], v[216:219], v[76:79]
	v_mfma_f32_16x16x32_bf16 v[72:75], v[192:195], v[216:219], v[72:75]
	v_mfma_f32_16x16x32_bf16 v[68:71], v[184:187], v[224:227], v[68:71]
	v_mfma_f32_16x16x32_bf16 v[64:67], v[192:195], v[224:227], v[64:67]
	s_setprio 0
	s_barrier
; #define PG8_STAGE(bufoff, gbase, voff) do { _Pragma("unroll") for (int _i = 0; _i < 2; ++_i) \
;         __builtin_amdgcn_global_load_lds((const unsigned*)((const char*)(gbase) + (voff)[_i]), (PG8_LAS unsigned*)(lds + (bufoff) + ldsw + _i * 8192), 16, 0, 0); } while (0)
; #define PG8_LDA(dst, b, h) do { _Pragma("unroll") for (int m = 0; m < 4; ++m) _Pragma("unroll") for (int k = 0; k < 2; ++k) dst[m][k] = *(const PG8_LAS bf16x8*)(lds + PG8_SA(b, h) + aoff + m * 2048 + k * 1024); } while (0)
; #define PG8_LDB(dst, b, h) do { _Pragma("unroll") for (int n = 0; n < 2; ++n) _Pragma("unroll") for (int k = 0; k < 2; ++k) dst[n][k] = *(const PG8_LAS bf16x8*)(lds + PG8_SB(b, h) + boff + n * 2048 + k * 1024); } while (0)
; template <class Epi, class Sched, bool ALIGN_EPI = false, bool SP2 = false>
; __device__ __forceinline__ void gemm_phase(PG8_LAS unsigned char* lds, const Gemm g, const Sched& S, const Epi& E) {
;     ...
;         for (int t = 0; t < nt; t += 2) {
;             const bool last = (t == nt - 2);
;             const char* a1 = cA + (size_t)(t + 1) * kstep;
;             const char* a2 = last ? nA : cA + (size_t)(t + 2) * kstep; const char* b2 = last ? nB : cB + (size_t)(t + 2) * kstep;
;             const char* a3 = a2 + kstep; const char* b3 = b2 + kstep;
;             if (last && has_next) S.a_ready(nxt);
;             if constexpr (SP2) {
;             PG8_LDB(B0, 0, 0); PG8_LDB(B1, 0, 1); PG8_SCHED; PG8_LDA(At, 0, 0); PG8_STAGE(PG8_SA(1, 1), a1 + hstep, voffA);
;             PG8_WAIT_V(8); PG8_WAIT_L(0); PG8_BAR; PG8_MMA(0, 0, At, B0); PG8_MMA(0, 1, At, B1); PG8_BAR; PG8_SCHED;
;             PG8_LDA(At, 0, 1); PG8_STAGE(PG8_SB(0, 0), b2, voffB); PG8_STAGE(PG8_SB(0, 1), b2 + hstep, voffB); PG8_STAGE(PG8_SA(0, 0), a2, voffA);
;             PG8_WAIT_V(8); PG8_WAIT_L(0); PG8_BAR; PG8_MMA(1, 0, At, B0); PG8_MMA(1, 1, At, B1); PG8_BAR; PG8_SCHED;
;             PG8_LDB(B0, 1, 0); PG8_LDB(B1, 1, 1); PG8_SCHED; PG8_LDA(At, 1, 0); PG8_STAGE(PG8_SA(0, 1), a2 + hstep, voffA);
;             PG8_WAIT_V(8); PG8_WAIT_L(0); PG8_BAR; PG8_MMA(0, 0, At, B0); PG8_MMA(0, 1, At, B1); PG8_BAR; PG8_SCHED;
;             PG8_LDA(At, 1, 1); PG8_STAGE(PG8_SB(1, 0), b3, voffB); PG8_STAGE(PG8_SB(1, 1), b3 + hstep, voffB); PG8_STAGE(PG8_SA(1, 0), a3, voffA);
;             PG8_WAIT_V(8); PG8_WAIT_L(0); PG8_BAR; PG8_MMA(1, 0, At, B0); PG8_MMA(1, 1, At, B1); PG8_BAR; PG8_SCHED;
	s_add_i32 s34, s57, s37
	v_lshl_add_u64 v[152:153], v[152:153], 0, s[14:15]
	s_mov_b32 m0, s34
	ds_read_b128 v[196:199], v163 offset:49152
	ds_read_b128 v[200:203], v163 offset:50176
	ds_read_b128 v[204:207], v163 offset:51200
	ds_read_b128 v[208:211], v163 offset:52224
	ds_read_b128 v[212:215], v163 offset:53248
	ds_read_b128 v[216:219], v163 offset:54272
	ds_read_b128 v[220:223], v163 offset:55296
	ds_read_b128 v[224:227], v163 offset:56320
	global_load_lds_dwordx4 v[152:153], off
	s_add_i32 m0, s34, 0x2000
	s_add_u32 s30, s30, 0x80080
	v_lshl_add_u64 v[152:153], v[228:229], 0, s[14:15]
	s_addc_u32 s31, s31, 0
	s_add_i32 s34, s58, s37
	global_load_lds_dwordx4 v[152:153], off
	v_lshl_add_u64 v[152:153], s[30:31], 0, v[130:131]
	s_mov_b32 m0, s34
	s_nop 0
	global_load_lds_dwordx4 v[152:153], off
	v_lshl_add_u64 v[152:153], s[30:31], 0, v[134:135]
	s_add_i32 m0, s34, 0x2000
	s_nop 0
	global_load_lds_dwordx4 v[152:153], off
	v_lshl_add_u64 v[152:153], v[230:231], 0, s[14:15]
	s_mov_b32 m0, s43
	s_nop 0
	global_load_lds_dwordx4 v[152:153], off
	v_lshl_add_u64 v[152:153], v[232:233], 0, s[14:15]
	s_mov_b32 m0, s44
	s_nop 0
	global_load_lds_dwordx4 v[152:153], off
	s_waitcnt vmcnt(8)
	s_waitcnt lgkmcnt(0)
	s_barrier
	s_setprio 1
	s_waitcnt lgkmcnt(0)
	v_mfma_f32_16x16x32_bf16 v[60:63], v[148:151], v[196:199], v[60:63]
	v_mfma_f32_16x16x32_bf16 v[56:59], v[170:173], v[196:199], v[56:59]
	v_mfma_f32_16x16x32_bf16 v[52:55], v[148:151], v[204:207], v[52:55]
	v_mfma_f32_16x16x32_bf16 v[48:51], v[170:173], v[204:207], v[48:51]
	v_mfma_f32_16x16x32_bf16 v[44:47], v[148:151], v[212:215], v[44:47]
	v_mfma_f32_16x16x32_bf16 v[40:43], v[170:173], v[212:215], v[40:43]
	v_mfma_f32_16x16x32_bf16 v[36:39], v[148:151], v[220:223], v[36:39]
	v_mfma_f32_16x16x32_bf16 v[32:35], v[170:173], v[220:223], v[32:35]
	v_mfma_f32_16x16x32_bf16 v[60:63], v[166:169], v[200:203], v[60:63]
	v_mfma_f32_16x16x32_bf16 v[56:59], v[174:177], v[200:203], v[56:59]
	v_mfma_f32_16x16x32_bf16 v[52:55], v[166:169], v[208:211], v[52:55]
	v_mfma_f32_16x16x32_bf16 v[48:51], v[174:177], v[208:211], v[48:51]
	v_mfma_f32_16x16x32_bf16 v[44:47], v[166:169], v[216:219], v[44:47]
	v_mfma_f32_16x16x32_bf16 v[40:43], v[174:177], v[216:219], v[40:43]
	v_mfma_f32_16x16x32_bf16 v[36:39], v[166:169], v[224:227], v[36:39]
	v_mfma_f32_16x16x32_bf16 v[32:35], v[174:177], v[224:227], v[32:35]
	s_setprio 0
	s_setprio 1
	v_mfma_f32_16x16x32_bf16 v[28:31], v[178:181], v[196:199], v[28:31]
	v_mfma_f32_16x16x32_bf16 v[24:27], v[188:191], v[196:199], v[24:27]
	v_mfma_f32_16x16x32_bf16 v[20:23], v[178:181], v[204:207], v[20:23]
	v_mfma_f32_16x16x32_bf16 v[16:19], v[188:191], v[204:207], v[16:19]
	v_mfma_f32_16x16x32_bf16 v[12:15], v[178:181], v[212:215], v[12:15]
	v_mfma_f32_16x16x32_bf16 v[8:11], v[188:191], v[212:215], v[8:11]
	v_mfma_f32_16x16x32_bf16 v[4:7], v[178:181], v[220:223], v[4:7]
	v_mfma_f32_16x16x32_bf16 v[0:3], v[188:191], v[220:223], v[0:3]
	v_mfma_f32_16x16x32_bf16 v[28:31], v[184:187], v[200:203], v[28:31]
	v_mfma_f32_16x16x32_bf16 v[24:27], v[192:195], v[200:203], v[24:27]
	v_mfma_f32_16x16x32_bf16 v[20:23], v[184:187], v[208:211], v[20:23]
	v_mfma_f32_16x16x32_bf16 v[16:19], v[192:195], v[208:211], v[16:19]
	v_mfma_f32_16x16x32_bf16 v[12:15], v[184:187], v[216:219], v[12:15]
	v_mfma_f32_16x16x32_bf16 v[8:11], v[192:195], v[216:219], v[8:11]
	v_mfma_f32_16x16x32_bf16 v[4:7], v[184:187], v[224:227], v[4:7]
	v_mfma_f32_16x16x32_bf16 v[0:3], v[192:195], v[224:227], v[0:3]
	s_add_i32 s56, s56, 2
	s_add_u32 s28, s28, 0x100
	s_addc_u32 s29, s29, 0
	s_add_u32 s54, s54, 0x100
	s_addc_u32 s55, s55, 0
	s_cmp_gt_u32 s56, 29
	s_setprio 0
	s_barrier
	s_cbranch_scc0 .LBB0_253
	s_and_b64 vcc, exec, s[16:17]
	s_cbranch_vccz .LBB0_256
	s_barrier

; #define PG8_STAGE(bufoff, gbase, voff) do { _Pragma("unroll") for (int _i = 0; _i < 2; ++_i) \
;         __builtin_amdgcn_global_load_lds((const unsigned*)((const char*)(gbase) + (voff)[_i]), (PG8_LAS unsigned*)(lds + (bufoff) + ldsw + _i * 8192), 16, 0, 0); } while (0)
; #define PG8_LDA(dst, b, h) do { _Pragma("unroll") for (int m = 0; m < 4; ++m) _Pragma("unroll") for (int k = 0; k < 2; ++k) dst[m][k] = *(const PG8_LAS bf16x8*)(lds + PG8_SA(b, h) + aoff + m * 2048 + k * 1024); } while (0)
; #define PG8_LDB(dst, b, h) do { _Pragma("unroll") for (int n = 0; n < 2; ++n) _Pragma("unroll") for (int k = 0; k < 2; ++k) dst[n][k] = *(const PG8_LAS bf16x8*)(lds + PG8_SB(b, h) + boff + n * 2048 + k * 1024); } while (0)
; #define PG8_MMA(ai, bj, At, Bt) do { __builtin_amdgcn_s_setprio(1); _Pragma("unroll") for (int m = 0; m < 4; ++m) _Pragma("unroll") for (int n = 0; n < 2; ++n) _Pragma("unroll") for (int k = 0; k < 2; ++k) \
;         acc[ai][bj][m][n] = __builtin_amdgcn_mfma_f32_16x16x32_bf16(Bt[n][k], At[m][k], acc[ai][bj][m][n], 0, 0, 0); __builtin_amdgcn_s_setprio(0); } while (0)
; #define PG8_WAIT_V(n) asm volatile("s_waitcnt vmcnt(" #n ")" ::: "memory")
; #define PG8_BAR __builtin_amdgcn_s_barrier()
; template <class Epi, class Sched, bool ALIGN_EPI = false, bool SP2 = false>
; __device__ __forceinline__ void gemm_phase(PG8_LAS unsigned char* lds, const Gemm g, const Sched& S, const Epi& E) {
;     ...
;         for (int t = 0; t < nt; t += 2) {
;             const bool last = (t == nt - 2);
;             const char* a1 = cA + (size_t)(t + 1) * kstep;
;             const char* a2 = last ? nA : cA + (size_t)(t + 2) * kstep; const char* b2 = last ? nB : cB + (size_t)(t + 2) * kstep;
;             const char* a3 = a2 + kstep; const char* b3 = b2 + kstep;
;             if (last && has_next) S.a_ready(nxt);
;             if constexpr (SP2) {
;             PG8_LDB(B0, 0, 0); PG8_LDB(B1, 0, 1); PG8_SCHED; PG8_LDA(At, 0, 0); PG8_STAGE(PG8_SA(1, 1), a1 + hstep, voffA);
;             PG8_WAIT_V(8); PG8_WAIT_L(0); PG8_BAR; PG8_MMA(0, 0, At, B0); PG8_MMA(0, 1, At, B1); PG8_BAR; PG8_SCHED;
;             PG8_LDA(At, 0, 1); PG8_STAGE(PG8_SB(0, 0), b2, voffB); PG8_STAGE(PG8_SB(0, 1), b2 + hstep, voffB); PG8_STAGE(PG8_SA(0, 0), a2, voffA);
;             PG8_WAIT_V(8); PG8_WAIT_L(0); PG8_BAR; PG8_MMA(1, 0, At, B0); PG8_MMA(1, 1, At, B1); PG8_BAR; PG8_SCHED;
.LBB0_953:
	v_add_u32_e32 v134, s50, v165
	ds_read_b128 v[144:147], v134
	ds_read_b128 v[148:151], v134 offset:1024
	ds_read_b128 v[170:173], v134 offset:2048
	ds_read_b128 v[174:177], v134 offset:3072
	v_add_u32_e32 v134, s51, v165
	ds_read_b128 v[178:181], v134
	ds_read_b128 v[184:187], v134 offset:1024
	ds_read_b128 v[188:191], v134 offset:2048
	ds_read_b128 v[192:195], v134 offset:3072
	s_add_u32 s34, s30, 0xfff80080
	s_addc_u32 s35, s31, -1
	s_cmp_eq_u32 s57, 28
	s_cselect_b32 s37, s21, s35
	s_cselect_b32 s36, s27, s34
	s_cselect_b32 s35, s19, s56
	s_cselect_b32 s34, s54, s55
	v_lshl_add_u64 v[152:153], s[30:31], 0, v[136:137]
	s_add_i32 m0, s29, 0xc000
	ds_read_b128 v[196:199], v167
	ds_read_b128 v[200:203], v167 offset:1024
	ds_read_b128 v[204:207], v167 offset:2048
	ds_read_b128 v[208:211], v167 offset:3072
	ds_read_b128 v[212:215], v167 offset:4096
	ds_read_b128 v[216:219], v167 offset:5120
	ds_read_b128 v[220:223], v167 offset:6144
	ds_read_b128 v[224:227], v167 offset:7168
	global_load_lds_dwordx4 v[152:153], off
	v_lshl_add_u64 v[152:153], s[30:31], 0, v[138:139]
	s_add_i32 m0, s29, 0xe000
	s_nop 0
	global_load_lds_dwordx4 v[152:153], off
	s_waitcnt vmcnt(8)
	s_waitcnt lgkmcnt(0)
	s_barrier
	s_setprio 1
	s_waitcnt lgkmcnt(0)
	v_mfma_f32_16x16x32_bf16 v[124:127], v[144:147], v[196:199], v[124:127]
	v_mfma_f32_16x16x32_bf16 v[120:123], v[170:173], v[196:199], v[120:123]
	v_mfma_f32_16x16x32_bf16 v[116:119], v[144:147], v[204:207], v[116:119]
	v_mfma_f32_16x16x32_bf16 v[112:115], v[170:173], v[204:207], v[112:115]
	v_mfma_f32_16x16x32_bf16 v[108:111], v[144:147], v[212:215], v[108:111]
	v_mfma_f32_16x16x32_bf16 v[104:107], v[170:173], v[212:215], v[104:107]
	v_mfma_f32_16x16x32_bf16 v[100:103], v[144:147], v[220:223], v[100:103]
	v_mfma_f32_16x16x32_bf16 v[96:99], v[170:173], v[220:223], v[96:99]
	v_mfma_f32_16x16x32_bf16 v[124:127], v[148:151], v[200:203], v[124:127]
	v_mfma_f32_16x16x32_bf16 v[120:123], v[174:177], v[200:203], v[120:123]
	v_mfma_f32_16x16x32_bf16 v[116:119], v[148:151], v[208:211], v[116:119]
	v_mfma_f32_16x16x32_bf16 v[112:115], v[174:177], v[208:211], v[112:115]
	v_mfma_f32_16x16x32_bf16 v[108:111], v[148:151], v[216:219], v[108:111]
	v_mfma_f32_16x16x32_bf16 v[104:107], v[174:177], v[216:219], v[104:107]
	v_mfma_f32_16x16x32_bf16 v[100:103], v[148:151], v[224:227], v[100:103]
	v_mfma_f32_16x16x32_bf16 v[96:99], v[174:177], v[224:227], v[96:99]
	s_setprio 0
	s_setprio 1
	v_mfma_f32_16x16x32_bf16 v[92:95], v[178:181], v[196:199], v[92:95]
	v_mfma_f32_16x16x32_bf16 v[88:91], v[188:191], v[196:199], v[88:91]
	v_mfma_f32_16x16x32_bf16 v[84:87], v[178:181], v[204:207], v[84:87]
	v_mfma_f32_16x16x32_bf16 v[80:83], v[188:191], v[204:207], v[80:83]
	v_mfma_f32_16x16x32_bf16 v[76:79], v[178:181], v[212:215], v[76:79]
	v_mfma_f32_16x16x32_bf16 v[72:75], v[188:191], v[212:215], v[72:75]
	v_mfma_f32_16x16x32_bf16 v[68:71], v[178:181], v[220:223], v[68:71]
	v_mfma_f32_16x16x32_bf16 v[64:67], v[188:191], v[220:223], v[64:67]
	v_mfma_f32_16x16x32_bf16 v[92:95], v[184:187], v[200:203], v[92:95]
	v_mfma_f32_16x16x32_bf16 v[88:91], v[192:195], v[200:203], v[88:91]
	v_mfma_f32_16x16x32_bf16 v[84:87], v[184:187], v[208:211], v[84:87]
	v_mfma_f32_16x16x32_bf16 v[80:83], v[192:195], v[208:211], v[80:83]
	v_mfma_f32_16x16x32_bf16 v[76:79], v[184:187], v[216:219], v[76:79]
	v_mfma_f32_16x16x32_bf16 v[72:75], v[192:195], v[216:219], v[72:75]
	v_mfma_f32_16x16x32_bf16 v[68:71], v[184:187], v[224:227], v[68:71]
	v_mfma_f32_16x16x32_bf16 v[64:67], v[192:195], v[224:227], v[64:67]
	s_setprio 0
	s_barrier
	s_add_i32 s58, s50, s41
	v_lshl_add_u64 v[152:153], s[34:35], 0, v[128:129]
	s_mov_b32 m0, s58
	ds_read_b128 v[196:199], v167 offset:16384
	ds_read_b128 v[200:203], v167 offset:17408
	ds_read_b128 v[204:207], v167 offset:18432
	ds_read_b128 v[208:211], v167 offset:19456
	ds_read_b128 v[212:215], v167 offset:20480
	ds_read_b128 v[216:219], v167 offset:21504
	ds_read_b128 v[220:223], v167 offset:22528
	ds_read_b128 v[224:227], v167 offset:23552
	global_load_lds_dwordx4 v[152:153], off
	s_add_i32 m0, s58, 0x2000
	s_add_u32 s58, s34, 0x80000
	v_lshl_add_u64 v[228:229], s[34:35], 0, v[130:131]
	s_addc_u32 s59, s35, 0
	s_add_i32 s60, s51, s41
	global_load_lds_dwordx4 v[228:229], off
	v_lshl_add_u64 v[230:231], s[58:59], 0, v[128:129]
	s_mov_b32 m0, s60
	v_lshl_add_u64 v[232:233], s[36:37], 0, v[130:131]
	global_load_lds_dwordx4 v[230:231], off
	v_lshl_add_u64 v[230:231], s[58:59], 0, v[130:131]
	s_add_i32 m0, s60, 0x2000
	s_nop 0
	global_load_lds_dwordx4 v[230:231], off
	v_lshl_add_u64 v[230:231], s[36:37], 0, v[128:129]
	s_mov_b32 m0, s29
	s_nop 0
	global_load_lds_dwordx4 v[230:231], off
	s_mov_b32 m0, s42
	s_nop 0
	global_load_lds_dwordx4 v[232:233], off
	s_waitcnt vmcnt(8)
	s_waitcnt lgkmcnt(0)
	s_barrier
; #define PG8_STAGE(bufoff, gbase, voff) do { _Pragma("unroll") for (int _i = 0; _i < 2; ++_i) \
;         __builtin_amdgcn_global_load_lds((const unsigned*)((const char*)(gbase) + (voff)[_i]), (PG8_LAS unsigned*)(lds + (bufoff) + ldsw + _i * 8192), 16, 0, 0); } while (0)
; #define PG8_LDA(dst, b, h) do { _Pragma("unroll") for (int m = 0; m < 4; ++m) _Pragma("unroll") for (int k = 0; k < 2; ++k) dst[m][k] = *(const PG8_LAS bf16x8*)(lds + PG8_SA(b, h) + aoff + m * 2048 + k * 1024); } while (0)
; #define PG8_LDB(dst, b, h) do { _Pragma("unroll") for (int n = 0; n < 2; ++n) _Pragma("unroll") for (int k = 0; k < 2; ++k) dst[n][k] = *(const PG8_LAS bf16x8*)(lds + PG8_SB(b, h) + boff + n * 2048 + k * 1024); } while (0)
; #define PG8_MMA(ai, bj, At, Bt) do { __builtin_amdgcn_s_setprio(1); _Pragma("unroll") for (int m = 0; m < 4; ++m) _Pragma("unroll") for (int n = 0; n < 2; ++n) _Pragma("unroll") for (int k = 0; k < 2; ++k) \
;         acc[ai][bj][m][n] = __builtin_amdgcn_mfma_f32_16x16x32_bf16(Bt[n][k], At[m][k], acc[ai][bj][m][n], 0, 0, 0); __builtin_amdgcn_s_setprio(0); } while (0)
; #define PG8_WAIT_V(n) asm volatile("s_waitcnt vmcnt(" #n ")" ::: "memory")
; #define PG8_WAIT_L(n) asm volatile("s_waitcnt lgkmcnt(" #n ")" ::: "memory")
; #define PG8_BAR __builtin_amdgcn_s_barrier()
; #define PG8_SCHED __builtin_amdgcn_sched_barrier(0)
; template <class Epi, class Sched, bool ALIGN_EPI = false, bool SP2 = false>
; __device__ __forceinline__ void gemm_phase(PG8_LAS unsigned char* lds, const Gemm g, const Sched& S, const Epi& E) {
;     ...
;             PG8_WAIT_V(8); PG8_WAIT_L(0); PG8_BAR; PG8_MMA(1, 0, At, B0); PG8_MMA(1, 1, At, B1); PG8_BAR; PG8_SCHED;
;             PG8_LDB(B0, 1, 0); PG8_LDB(B1, 1, 1); PG8_SCHED; PG8_LDA(At, 1, 0); PG8_STAGE(PG8_SA(0, 1), a2 + hstep, voffA);
;             PG8_WAIT_V(8); PG8_WAIT_L(0); PG8_BAR; PG8_MMA(0, 0, At, B0); PG8_MMA(0, 1, At, B1); PG8_BAR; PG8_SCHED;
	s_setprio 1
	s_waitcnt lgkmcnt(0)
	v_mfma_f32_16x16x32_bf16 v[60:63], v[144:147], v[196:199], v[60:63]
	v_mfma_f32_16x16x32_bf16 v[56:59], v[170:173], v[196:199], v[56:59]
	v_mfma_f32_16x16x32_bf16 v[52:55], v[144:147], v[204:207], v[52:55]
	v_mfma_f32_16x16x32_bf16 v[48:51], v[170:173], v[204:207], v[48:51]
	v_mfma_f32_16x16x32_bf16 v[44:47], v[144:147], v[212:215], v[44:47]
	v_mfma_f32_16x16x32_bf16 v[40:43], v[170:173], v[212:215], v[40:43]
	v_mfma_f32_16x16x32_bf16 v[36:39], v[144:147], v[220:223], v[36:39]
	v_mfma_f32_16x16x32_bf16 v[32:35], v[170:173], v[220:223], v[32:35]
	v_mfma_f32_16x16x32_bf16 v[60:63], v[148:151], v[200:203], v[60:63]
	v_mfma_f32_16x16x32_bf16 v[56:59], v[174:177], v[200:203], v[56:59]
	v_mfma_f32_16x16x32_bf16 v[52:55], v[148:151], v[208:211], v[52:55]
	v_mfma_f32_16x16x32_bf16 v[48:51], v[174:177], v[208:211], v[48:51]
	v_mfma_f32_16x16x32_bf16 v[44:47], v[148:151], v[216:219], v[44:47]
	v_mfma_f32_16x16x32_bf16 v[40:43], v[174:177], v[216:219], v[40:43]
	v_mfma_f32_16x16x32_bf16 v[36:39], v[148:151], v[224:227], v[36:39]
	v_mfma_f32_16x16x32_bf16 v[32:35], v[174:177], v[224:227], v[32:35]
	s_setprio 0
	s_setprio 1
	v_mfma_f32_16x16x32_bf16 v[28:31], v[178:181], v[196:199], v[28:31]
	v_mfma_f32_16x16x32_bf16 v[24:27], v[188:191], v[196:199], v[24:27]
	v_mfma_f32_16x16x32_bf16 v[20:23], v[178:181], v[204:207], v[20:23]
	v_mfma_f32_16x16x32_bf16 v[16:19], v[188:191], v[204:207], v[16:19]
	v_mfma_f32_16x16x32_bf16 v[12:15], v[178:181], v[212:215], v[12:15]
	v_mfma_f32_16x16x32_bf16 v[8:11], v[188:191], v[212:215], v[8:11]
	v_mfma_f32_16x16x32_bf16 v[4:7], v[178:181], v[220:223], v[4:7]
	v_mfma_f32_16x16x32_bf16 v[0:3], v[188:191], v[220:223], v[0:3]
	v_mfma_f32_16x16x32_bf16 v[28:31], v[184:187], v[200:203], v[28:31]
	v_mfma_f32_16x16x32_bf16 v[24:27], v[192:195], v[200:203], v[24:27]
	v_mfma_f32_16x16x32_bf16 v[20:23], v[184:187], v[208:211], v[20:23]
	v_mfma_f32_16x16x32_bf16 v[16:19], v[192:195], v[208:211], v[16:19]
	v_mfma_f32_16x16x32_bf16 v[12:15], v[184:187], v[216:219], v[12:15]
	v_mfma_f32_16x16x32_bf16 v[8:11], v[192:195], v[216:219], v[8:11]
	v_mfma_f32_16x16x32_bf16 v[4:7], v[184:187], v[224:227], v[4:7]
	v_mfma_f32_16x16x32_bf16 v[0:3], v[192:195], v[224:227], v[0:3]
	s_setprio 0
	s_barrier
	s_add_i32 s58, 0, 0x18000
	v_add_u32_e32 v134, s58, v165
	s_add_i32 s59, 0, 0x1c000
	ds_read_b128 v[144:147], v134
	ds_read_b128 v[148:151], v134 offset:1024
	ds_read_b128 v[170:173], v134 offset:2048
	ds_read_b128 v[174:177], v134 offset:3072
	v_add_u32_e32 v134, s59, v165
	ds_read_b128 v[178:181], v134
	ds_read_b128 v[184:187], v134 offset:1024
	ds_read_b128 v[188:191], v134 offset:2048
	ds_read_b128 v[192:195], v134 offset:3072
	s_add_u32 s36, s36, 0x80000
	s_addc_u32 s37, s37, 0
	s_mov_b32 m0, s43
	v_lshl_add_u64 v[234:235], s[36:37], 0, v[128:129]
	ds_read_b128 v[196:199], v167 offset:32768
	ds_read_b128 v[200:203], v167 offset:33792
	ds_read_b128 v[204:207], v167 offset:34816
	ds_read_b128 v[208:211], v167 offset:35840
	ds_read_b128 v[212:215], v167 offset:36864
	ds_read_b128 v[216:219], v167 offset:37888
	ds_read_b128 v[220:223], v167 offset:38912
	ds_read_b128 v[224:227], v167 offset:39936
	global_load_lds_dwordx4 v[234:235], off
	v_lshl_add_u64 v[234:235], s[36:37], 0, v[130:131]
	s_mov_b32 m0, s44
	s_nop 0
	global_load_lds_dwordx4 v[234:235], off
	s_waitcnt vmcnt(8)
	s_waitcnt lgkmcnt(0)
	s_barrier
	s_setprio 1
	s_waitcnt lgkmcnt(0)
	v_mfma_f32_16x16x32_bf16 v[124:127], v[144:147], v[196:199], v[124:127]
	v_mfma_f32_16x16x32_bf16 v[120:123], v[170:173], v[196:199], v[120:123]
	v_mfma_f32_16x16x32_bf16 v[116:119], v[144:147], v[204:207], v[116:119]
	v_mfma_f32_16x16x32_bf16 v[112:115], v[170:173], v[204:207], v[112:115]
	v_mfma_f32_16x16x32_bf16 v[108:111], v[144:147], v[212:215], v[108:111]
	v_mfma_f32_16x16x32_bf16 v[104:107], v[170:173], v[212:215], v[104:107]
	v_mfma_f32_16x16x32_bf16 v[100:103], v[144:147], v[220:223], v[100:103]
	v_mfma_f32_16x16x32_bf16 v[96:99], v[170:173], v[220:223], v[96:99]
	v_mfma_f32_16x16x32_bf16 v[124:127], v[148:151], v[200:203], v[124:127]
	v_mfma_f32_16x16x32_bf16 v[120:123], v[174:177], v[200:203], v[120:123]
	v_mfma_f32_16x16x32_bf16 v[116:119], v[148:151], v[208:211], v[116:119]
	v_mfma_f32_16x16x32_bf16 v[112:115], v[174:177], v[208:211], v[112:115]
	v_mfma_f32_16x16x32_bf16 v[108:111], v[148:151], v[216:219], v[108:111]
	v_mfma_f32_16x16x32_bf16 v[104:107], v[174:177], v[216:219], v[104:107]
	v_mfma_f32_16x16x32_bf16 v[100:103], v[148:151], v[224:227], v[100:103]
	v_mfma_f32_16x16x32_bf16 v[96:99], v[174:177], v[224:227], v[96:99]
	s_setprio 0
	s_setprio 1
	v_mfma_f32_16x16x32_bf16 v[92:95], v[178:181], v[196:199], v[92:95]
	v_mfma_f32_16x16x32_bf16 v[88:91], v[188:191], v[196:199], v[88:91]
	v_mfma_f32_16x16x32_bf16 v[84:87], v[178:181], v[204:207], v[84:87]
	v_mfma_f32_16x16x32_bf16 v[80:83], v[188:191], v[204:207], v[80:83]
	v_mfma_f32_16x16x32_bf16 v[76:79], v[178:181], v[212:215], v[76:79]
	v_mfma_f32_16x16x32_bf16 v[72:75], v[188:191], v[212:215], v[72:75]
	v_mfma_f32_16x16x32_bf16 v[68:71], v[178:181], v[220:223], v[68:71]
	v_mfma_f32_16x16x32_bf16 v[64:67], v[188:191], v[220:223], v[64:67]
	v_mfma_f32_16x16x32_bf16 v[92:95], v[184:187], v[200:203], v[92:95]
	v_mfma_f32_16x16x32_bf16 v[88:91], v[192:195], v[200:203], v[88:91]
	v_mfma_f32_16x16x32_bf16 v[84:87], v[184:187], v[208:211], v[84:87]
	v_mfma_f32_16x16x32_bf16 v[80:83], v[192:195], v[208:211], v[80:83]
	v_mfma_f32_16x16x32_bf16 v[76:79], v[184:187], v[216:219], v[76:79]
	v_mfma_f32_16x16x32_bf16 v[72:75], v[192:195], v[216:219], v[72:75]
	v_mfma_f32_16x16x32_bf16 v[68:71], v[184:187], v[224:227], v[68:71]
	v_mfma_f32_16x16x32_bf16 v[64:67], v[192:195], v[224:227], v[64:67]
	s_setprio 0
	s_barrier
; #define PG8_STAGE(bufoff, gbase, voff) do { _Pragma("unroll") for (int _i = 0; _i < 2; ++_i) \
;         __builtin_amdgcn_global_load_lds((const unsigned*)((const char*)(gbase) + (voff)[_i]), (PG8_LAS unsigned*)(lds + (bufoff) + ldsw + _i * 8192), 16, 0, 0); } while (0)
; #define PG8_LDA(dst, b, h) do { _Pragma("unroll") for (int m = 0; m < 4; ++m) _Pragma("unroll") for (int k = 0; k < 2; ++k) dst[m][k] = *(const PG8_LAS bf16x8*)(lds + PG8_SA(b, h) + aoff + m * 2048 + k * 1024); } while (0)
; #define PG8_LDB(dst, b, h) do { _Pragma("unroll") for (int n = 0; n < 2; ++n) _Pragma("unroll") for (int k = 0; k < 2; ++k) dst[n][k] = *(const PG8_LAS bf16x8*)(lds + PG8_SB(b, h) + boff + n * 2048 + k * 1024); } while (0)
; template <class Epi, class Sched, bool ALIGN_EPI = false, bool SP2 = false>
; __device__ __forceinline__ void gemm_phase(PG8_LAS unsigned char* lds, const Gemm g, const Sched& S, const Epi& E) {
;     ...
;         for (int t = 0; t < nt; t += 2) {
;             const bool last = (t == nt - 2);
;             const char* a1 = cA + (size_t)(t + 1) * kstep;
;             const char* a2 = last ? nA : cA + (size_t)(t + 2) * kstep; const char* b2 = last ? nB : cB + (size_t)(t + 2) * kstep;
;             const char* a3 = a2 + kstep; const char* b3 = b2 + kstep;
;             if (last && has_next) S.a_ready(nxt);
;             if constexpr (SP2) {
;             PG8_LDB(B0, 0, 0); PG8_LDB(B1, 0, 1); PG8_SCHED; PG8_LDA(At, 0, 0); PG8_STAGE(PG8_SA(1, 1), a1 + hstep, voffA);
;             PG8_WAIT_V(8); PG8_WAIT_L(0); PG8_BAR; PG8_MMA(0, 0, At, B0); PG8_MMA(0, 1, At, B1); PG8_BAR; PG8_SCHED;
;             PG8_LDA(At, 0, 1); PG8_STAGE(PG8_SB(0, 0), b2, voffB); PG8_STAGE(PG8_SB(0, 1), b2 + hstep, voffB); PG8_STAGE(PG8_SA(0, 0), a2, voffA);
;             PG8_WAIT_V(8); PG8_WAIT_L(0); PG8_BAR; PG8_MMA(1, 0, At, B0); PG8_MMA(1, 1, At, B1); PG8_BAR; PG8_SCHED;
;             PG8_LDB(B0, 1, 0); PG8_LDB(B1, 1, 1); PG8_SCHED; PG8_LDA(At, 1, 0); PG8_STAGE(PG8_SA(0, 1), a2 + hstep, voffA);
;             PG8_WAIT_V(8); PG8_WAIT_L(0); PG8_BAR; PG8_MMA(0, 0, At, B0); PG8_MMA(0, 1, At, B1); PG8_BAR; PG8_SCHED;
;             PG8_LDA(At, 1, 1); PG8_STAGE(PG8_SB(1, 0), b3, voffB); PG8_STAGE(PG8_SB(1, 1), b3 + hstep, voffB); PG8_STAGE(PG8_SA(1, 0), a3, voffA);
;             PG8_WAIT_V(8); PG8_WAIT_L(0); PG8_BAR; PG8_MMA(1, 0, At, B0); PG8_MMA(1, 1, At, B1); PG8_BAR; PG8_SCHED;
	s_add_i32 s36, s58, s41
	v_lshl_add_u64 v[152:153], v[152:153], 0, s[14:15]
	s_mov_b32 m0, s36
	ds_read_b128 v[196:199], v167 offset:49152
	ds_read_b128 v[200:203], v167 offset:50176
	ds_read_b128 v[204:207], v167 offset:51200
	ds_read_b128 v[208:211], v167 offset:52224
	ds_read_b128 v[212:215], v167 offset:53248
	ds_read_b128 v[216:219], v167 offset:54272
	ds_read_b128 v[220:223], v167 offset:55296
	ds_read_b128 v[224:227], v167 offset:56320
	global_load_lds_dwordx4 v[152:153], off
	s_add_i32 m0, s36, 0x2000
	s_add_u32 s34, s34, 0x80080
	v_lshl_add_u64 v[152:153], v[228:229], 0, s[14:15]
	s_addc_u32 s35, s35, 0
	s_add_i32 s36, s59, s41
	global_load_lds_dwordx4 v[152:153], off
	v_lshl_add_u64 v[152:153], s[34:35], 0, v[128:129]
	s_mov_b32 m0, s36
	s_nop 0
	global_load_lds_dwordx4 v[152:153], off
	v_lshl_add_u64 v[152:153], s[34:35], 0, v[130:131]
	s_add_i32 m0, s36, 0x2000
	s_nop 0
	global_load_lds_dwordx4 v[152:153], off
	v_lshl_add_u64 v[152:153], v[230:231], 0, s[14:15]
	s_mov_b32 m0, s45
	s_nop 0
	global_load_lds_dwordx4 v[152:153], off
	v_lshl_add_u64 v[152:153], v[232:233], 0, s[14:15]
	s_mov_b32 m0, s46
	s_nop 0
	global_load_lds_dwordx4 v[152:153], off
	s_waitcnt vmcnt(8)
	s_waitcnt lgkmcnt(0)
	s_barrier
	s_setprio 1
	s_waitcnt lgkmcnt(0)
	v_mfma_f32_16x16x32_bf16 v[60:63], v[144:147], v[196:199], v[60:63]
	v_mfma_f32_16x16x32_bf16 v[56:59], v[170:173], v[196:199], v[56:59]
	v_mfma_f32_16x16x32_bf16 v[52:55], v[144:147], v[204:207], v[52:55]
	v_mfma_f32_16x16x32_bf16 v[48:51], v[170:173], v[204:207], v[48:51]
	v_mfma_f32_16x16x32_bf16 v[44:47], v[144:147], v[212:215], v[44:47]
	v_mfma_f32_16x16x32_bf16 v[40:43], v[170:173], v[212:215], v[40:43]
	v_mfma_f32_16x16x32_bf16 v[36:39], v[144:147], v[220:223], v[36:39]
	v_mfma_f32_16x16x32_bf16 v[32:35], v[170:173], v[220:223], v[32:35]
	v_mfma_f32_16x16x32_bf16 v[60:63], v[148:151], v[200:203], v[60:63]
	v_mfma_f32_16x16x32_bf16 v[56:59], v[174:177], v[200:203], v[56:59]
	v_mfma_f32_16x16x32_bf16 v[52:55], v[148:151], v[208:211], v[52:55]
	v_mfma_f32_16x16x32_bf16 v[48:51], v[174:177], v[208:211], v[48:51]
	v_mfma_f32_16x16x32_bf16 v[44:47], v[148:151], v[216:219], v[44:47]
	v_mfma_f32_16x16x32_bf16 v[40:43], v[174:177], v[216:219], v[40:43]
	v_mfma_f32_16x16x32_bf16 v[36:39], v[148:151], v[224:227], v[36:39]
	v_mfma_f32_16x16x32_bf16 v[32:35], v[174:177], v[224:227], v[32:35]
	s_setprio 0
	s_setprio 1
	v_mfma_f32_16x16x32_bf16 v[28:31], v[178:181], v[196:199], v[28:31]
	v_mfma_f32_16x16x32_bf16 v[24:27], v[188:191], v[196:199], v[24:27]
	v_mfma_f32_16x16x32_bf16 v[20:23], v[178:181], v[204:207], v[20:23]
	v_mfma_f32_16x16x32_bf16 v[16:19], v[188:191], v[204:207], v[16:19]
	v_mfma_f32_16x16x32_bf16 v[12:15], v[178:181], v[212:215], v[12:15]
	v_mfma_f32_16x16x32_bf16 v[8:11], v[188:191], v[212:215], v[8:11]
	v_mfma_f32_16x16x32_bf16 v[4:7], v[178:181], v[220:223], v[4:7]
	v_mfma_f32_16x16x32_bf16 v[0:3], v[188:191], v[220:223], v[0:3]
	v_mfma_f32_16x16x32_bf16 v[28:31], v[184:187], v[200:203], v[28:31]
	v_mfma_f32_16x16x32_bf16 v[24:27], v[192:195], v[200:203], v[24:27]
	v_mfma_f32_16x16x32_bf16 v[20:23], v[184:187], v[208:211], v[20:23]
	v_mfma_f32_16x16x32_bf16 v[16:19], v[192:195], v[208:211], v[16:19]
	v_mfma_f32_16x16x32_bf16 v[12:15], v[184:187], v[216:219], v[12:15]
	v_mfma_f32_16x16x32_bf16 v[8:11], v[192:195], v[216:219], v[8:11]
	v_mfma_f32_16x16x32_bf16 v[4:7], v[184:187], v[224:227], v[4:7]
	v_mfma_f32_16x16x32_bf16 v[0:3], v[192:195], v[224:227], v[0:3]
	s_add_i32 s57, s57, 2
	s_add_u32 s30, s30, 0x100
	s_addc_u32 s31, s31, 0
	s_add_u32 s55, s55, 0x100
	s_addc_u32 s56, s56, 0
	s_cmp_gt_u32 s57, 29
	s_setprio 0
	s_barrier
	s_cbranch_scc0 .LBB0_953
	s_and_b64 vcc, exec, s[16:17]
	s_cbranch_vccz .LBB0_956
	s_barrier

; #define PG8_STAGE(bufoff, gbase, voff) do { _Pragma("unroll") for (int _i = 0; _i < 2; ++_i) \
;         __builtin_amdgcn_global_load_lds((const unsigned*)((const char*)(gbase) + (voff)[_i]), (PG8_LAS unsigned*)(lds + (bufoff) + ldsw + _i * 8192), 16, 0, 0); } while (0)
; #define PG8_LDA(dst, b, h) do { _Pragma("unroll") for (int m = 0; m < 4; ++m) _Pragma("unroll") for (int k = 0; k < 2; ++k) dst[m][k] = *(const PG8_LAS bf16x8*)(lds + PG8_SA(b, h) + aoff + m * 2048 + k * 1024); } while (0)
; #define PG8_LDB(dst, b, h) do { _Pragma("unroll") for (int n = 0; n < 2; ++n) _Pragma("unroll") for (int k = 0; k < 2; ++k) dst[n][k] = *(const PG8_LAS bf16x8*)(lds + PG8_SB(b, h) + boff + n * 2048 + k * 1024); } while (0)
; #define PG8_MMA(ai, bj, At, Bt) do { __builtin_amdgcn_s_setprio(1); _Pragma("unroll") for (int m = 0; m < 4; ++m) _Pragma("unroll") for (int n = 0; n < 2; ++n) _Pragma("unroll") for (int k = 0; k < 2; ++k) \
;         acc[ai][bj][m][n] = __builtin_amdgcn_mfma_f32_16x16x32_bf16(Bt[n][k], At[m][k], acc[ai][bj][m][n], 0, 0, 0); __builtin_amdgcn_s_setprio(0); } while (0)
; #define PG8_WAIT_V(n) asm volatile("s_waitcnt vmcnt(" #n ")" ::: "memory")
; #define PG8_BAR __builtin_amdgcn_s_barrier()
; template <class Epi, class Sched, bool ALIGN_EPI = false, bool SP2 = false>
; __device__ __forceinline__ void gemm_phase(PG8_LAS unsigned char* lds, const Gemm g, const Sched& S, const Epi& E) {
;     ...
;         for (int t = 0; t < nt; t += 2) {
;             const bool last = (t == nt - 2);
;             const char* a1 = cA + (size_t)(t + 1) * kstep;
;             const char* a2 = last ? nA : cA + (size_t)(t + 2) * kstep; const char* b2 = last ? nB : cB + (size_t)(t + 2) * kstep;
;             const char* a3 = a2 + kstep; const char* b3 = b2 + kstep;
;             if (last && has_next) S.a_ready(nxt);
;             if constexpr (SP2) {
;             PG8_LDB(B0, 0, 0); PG8_LDB(B1, 0, 1); PG8_SCHED; PG8_LDA(At, 0, 0); PG8_STAGE(PG8_SA(1, 1), a1 + hstep, voffA);
;             PG8_WAIT_V(8); PG8_WAIT_L(0); PG8_BAR; PG8_MMA(0, 0, At, B0); PG8_MMA(0, 1, At, B1); PG8_BAR; PG8_SCHED;
;             PG8_LDA(At, 0, 1); PG8_STAGE(PG8_SB(0, 0), b2, voffB); PG8_STAGE(PG8_SB(0, 1), b2 + hstep, voffB); PG8_STAGE(PG8_SA(0, 0), a2, voffA);
;             PG8_WAIT_V(8); PG8_WAIT_L(0); PG8_BAR; PG8_MMA(1, 0, At, B0); PG8_MMA(1, 1, At, B1); PG8_BAR; PG8_SCHED;
.LBB0_1071:
	ds_read_b128 v[148:151], v162
	ds_read_b128 v[170:173], v162 offset:1024
	ds_read_b128 v[174:177], v162 offset:2048
	ds_read_b128 v[178:181], v162 offset:3072
	ds_read_b128 v[184:187], v163
	ds_read_b128 v[188:191], v163 offset:1024
	ds_read_b128 v[192:195], v163 offset:2048
	ds_read_b128 v[196:199], v163 offset:3072
	s_add_u32 s34, s30, 0xfff80080
	s_addc_u32 s35, s31, -1
	s_cmp_eq_u32 s58, 28
	s_cselect_b32 s37, s21, s35
	s_cselect_b32 s36, s29, s34
	s_cselect_b32 s35, s19, s57
	s_cselect_b32 s34, s55, s56
	v_lshl_add_u64 v[152:153], s[30:31], 0, v[140:141]
	s_add_i32 m0, s27, 0xc000
	ds_read_b128 v[200:203], v164
	ds_read_b128 v[204:207], v164 offset:1024
	ds_read_b128 v[208:211], v164 offset:2048
	ds_read_b128 v[212:215], v164 offset:3072
	ds_read_b128 v[216:219], v164 offset:4096
	ds_read_b128 v[220:223], v164 offset:5120
	ds_read_b128 v[224:227], v164 offset:6144
	ds_read_b128 v[228:231], v164 offset:7168
	global_load_lds_dwordx4 v[152:153], off
	v_lshl_add_u64 v[152:153], s[30:31], 0, v[142:143]
	s_add_i32 m0, s27, 0xe000
	s_nop 0
	global_load_lds_dwordx4 v[152:153], off
	s_waitcnt vmcnt(8)
	s_waitcnt lgkmcnt(0)
	s_barrier
	s_setprio 1
	s_waitcnt lgkmcnt(0)
	v_mfma_f32_16x16x32_bf16 v[124:127], v[148:151], v[200:203], v[124:127]
	v_mfma_f32_16x16x32_bf16 v[120:123], v[174:177], v[200:203], v[120:123]
	v_mfma_f32_16x16x32_bf16 v[116:119], v[148:151], v[208:211], v[116:119]
	v_mfma_f32_16x16x32_bf16 v[112:115], v[174:177], v[208:211], v[112:115]
	v_mfma_f32_16x16x32_bf16 v[108:111], v[148:151], v[216:219], v[108:111]
	v_mfma_f32_16x16x32_bf16 v[104:107], v[174:177], v[216:219], v[104:107]
	v_mfma_f32_16x16x32_bf16 v[100:103], v[148:151], v[224:227], v[100:103]
	v_mfma_f32_16x16x32_bf16 v[96:99], v[174:177], v[224:227], v[96:99]
	v_mfma_f32_16x16x32_bf16 v[124:127], v[170:173], v[204:207], v[124:127]
	v_mfma_f32_16x16x32_bf16 v[120:123], v[178:181], v[204:207], v[120:123]
	v_mfma_f32_16x16x32_bf16 v[116:119], v[170:173], v[212:215], v[116:119]
	v_mfma_f32_16x16x32_bf16 v[112:115], v[178:181], v[212:215], v[112:115]
	v_mfma_f32_16x16x32_bf16 v[108:111], v[170:173], v[220:223], v[108:111]
	v_mfma_f32_16x16x32_bf16 v[104:107], v[178:181], v[220:223], v[104:107]
	v_mfma_f32_16x16x32_bf16 v[100:103], v[170:173], v[228:231], v[100:103]
	v_mfma_f32_16x16x32_bf16 v[96:99], v[178:181], v[228:231], v[96:99]
	s_setprio 0
	s_setprio 1
	v_mfma_f32_16x16x32_bf16 v[92:95], v[184:187], v[200:203], v[92:95]
	v_mfma_f32_16x16x32_bf16 v[88:91], v[192:195], v[200:203], v[88:91]
	v_mfma_f32_16x16x32_bf16 v[84:87], v[184:187], v[208:211], v[84:87]
	v_mfma_f32_16x16x32_bf16 v[80:83], v[192:195], v[208:211], v[80:83]
	v_mfma_f32_16x16x32_bf16 v[76:79], v[184:187], v[216:219], v[76:79]
	v_mfma_f32_16x16x32_bf16 v[72:75], v[192:195], v[216:219], v[72:75]
	v_mfma_f32_16x16x32_bf16 v[68:71], v[184:187], v[224:227], v[68:71]
	v_mfma_f32_16x16x32_bf16 v[64:67], v[192:195], v[224:227], v[64:67]
	v_mfma_f32_16x16x32_bf16 v[92:95], v[188:191], v[204:207], v[92:95]
	v_mfma_f32_16x16x32_bf16 v[88:91], v[196:199], v[204:207], v[88:91]
	v_mfma_f32_16x16x32_bf16 v[84:87], v[188:191], v[212:215], v[84:87]
	v_mfma_f32_16x16x32_bf16 v[80:83], v[196:199], v[212:215], v[80:83]
	v_mfma_f32_16x16x32_bf16 v[76:79], v[188:191], v[220:223], v[76:79]
	v_mfma_f32_16x16x32_bf16 v[72:75], v[196:199], v[220:223], v[72:75]
	v_mfma_f32_16x16x32_bf16 v[68:71], v[188:191], v[228:231], v[68:71]
	v_mfma_f32_16x16x32_bf16 v[64:67], v[196:199], v[228:231], v[64:67]
	s_setprio 0
	s_barrier
	s_add_i32 s59, s52, s33
	v_lshl_add_u64 v[152:153], s[34:35], 0, v[130:131]
	s_mov_b32 m0, s59
	ds_read_b128 v[200:203], v164 offset:16384
	ds_read_b128 v[204:207], v164 offset:17408
	ds_read_b128 v[208:211], v164 offset:18432
	ds_read_b128 v[212:215], v164 offset:19456
	ds_read_b128 v[216:219], v164 offset:20480
	ds_read_b128 v[220:223], v164 offset:21504
	ds_read_b128 v[224:227], v164 offset:22528
	ds_read_b128 v[228:231], v164 offset:23552
	global_load_lds_dwordx4 v[152:153], off
	s_add_i32 m0, s59, 0x2000
	s_add_u32 s60, s34, 0x80000
	v_lshl_add_u64 v[232:233], s[34:35], 0, v[134:135]
	s_addc_u32 s61, s35, 0
	s_add_i32 s59, s53, s33
	global_load_lds_dwordx4 v[232:233], off
	v_lshl_add_u64 v[234:235], s[60:61], 0, v[130:131]
	s_mov_b32 m0, s59
	v_lshl_add_u64 v[236:237], s[36:37], 0, v[132:133]
	global_load_lds_dwordx4 v[234:235], off
	v_lshl_add_u64 v[234:235], s[60:61], 0, v[134:135]
	s_add_i32 m0, s59, 0x2000
	s_nop 0
	global_load_lds_dwordx4 v[234:235], off
	v_lshl_add_u64 v[234:235], s[36:37], 0, v[128:129]
	s_mov_b32 m0, s27
	s_nop 0
	global_load_lds_dwordx4 v[234:235], off
	s_mov_b32 m0, s42
	s_nop 0
	global_load_lds_dwordx4 v[236:237], off
	s_waitcnt vmcnt(8)
	s_waitcnt lgkmcnt(0)
	s_barrier
; #define PG8_STAGE(bufoff, gbase, voff) do { _Pragma("unroll") for (int _i = 0; _i < 2; ++_i) \
;         __builtin_amdgcn_global_load_lds((const unsigned*)((const char*)(gbase) + (voff)[_i]), (PG8_LAS unsigned*)(lds + (bufoff) + ldsw + _i * 8192), 16, 0, 0); } while (0)
; #define PG8_LDA(dst, b, h) do { _Pragma("unroll") for (int m = 0; m < 4; ++m) _Pragma("unroll") for (int k = 0; k < 2; ++k) dst[m][k] = *(const PG8_LAS bf16x8*)(lds + PG8_SA(b, h) + aoff + m * 2048 + k * 1024); } while (0)
; #define PG8_LDB(dst, b, h) do { _Pragma("unroll") for (int n = 0; n < 2; ++n) _Pragma("unroll") for (int k = 0; k < 2; ++k) dst[n][k] = *(const PG8_LAS bf16x8*)(lds + PG8_SB(b, h) + boff + n * 2048 + k * 1024); } while (0)
; #define PG8_MMA(ai, bj, At, Bt) do { __builtin_amdgcn_s_setprio(1); _Pragma("unroll") for (int m = 0; m < 4; ++m) _Pragma("unroll") for (int n = 0; n < 2; ++n) _Pragma("unroll") for (int k = 0; k < 2; ++k) \
;         acc[ai][bj][m][n] = __builtin_amdgcn_mfma_f32_16x16x32_bf16(Bt[n][k], At[m][k], acc[ai][bj][m][n], 0, 0, 0); __builtin_amdgcn_s_setprio(0); } while (0)
; #define PG8_WAIT_V(n) asm volatile("s_waitcnt vmcnt(" #n ")" ::: "memory")
; #define PG8_WAIT_L(n) asm volatile("s_waitcnt lgkmcnt(" #n ")" ::: "memory")
; #define PG8_BAR __builtin_amdgcn_s_barrier()
; #define PG8_SCHED __builtin_amdgcn_sched_barrier(0)
; template <class Epi, class Sched, bool ALIGN_EPI = false, bool SP2 = false>
; __device__ __forceinline__ void gemm_phase(PG8_LAS unsigned char* lds, const Gemm g, const Sched& S, const Epi& E) {
;     ...
;             PG8_WAIT_V(8); PG8_WAIT_L(0); PG8_BAR; PG8_MMA(1, 0, At, B0); PG8_MMA(1, 1, At, B1); PG8_BAR; PG8_SCHED;
;             PG8_LDB(B0, 1, 0); PG8_LDB(B1, 1, 1); PG8_SCHED; PG8_LDA(At, 1, 0); PG8_STAGE(PG8_SA(0, 1), a2 + hstep, voffA);
;             PG8_WAIT_V(8); PG8_WAIT_L(0); PG8_BAR; PG8_MMA(0, 0, At, B0); PG8_MMA(0, 1, At, B1); PG8_BAR; PG8_SCHED;
	s_setprio 1
	s_waitcnt lgkmcnt(0)
	v_mfma_f32_16x16x32_bf16 v[60:63], v[148:151], v[200:203], v[60:63]
	v_mfma_f32_16x16x32_bf16 v[56:59], v[174:177], v[200:203], v[56:59]
	v_mfma_f32_16x16x32_bf16 v[52:55], v[148:151], v[208:211], v[52:55]
	v_mfma_f32_16x16x32_bf16 v[48:51], v[174:177], v[208:211], v[48:51]
	v_mfma_f32_16x16x32_bf16 v[44:47], v[148:151], v[216:219], v[44:47]
	v_mfma_f32_16x16x32_bf16 v[40:43], v[174:177], v[216:219], v[40:43]
	v_mfma_f32_16x16x32_bf16 v[36:39], v[148:151], v[224:227], v[36:39]
	v_mfma_f32_16x16x32_bf16 v[32:35], v[174:177], v[224:227], v[32:35]
	v_mfma_f32_16x16x32_bf16 v[60:63], v[170:173], v[204:207], v[60:63]
	v_mfma_f32_16x16x32_bf16 v[56:59], v[178:181], v[204:207], v[56:59]
	v_mfma_f32_16x16x32_bf16 v[52:55], v[170:173], v[212:215], v[52:55]
	v_mfma_f32_16x16x32_bf16 v[48:51], v[178:181], v[212:215], v[48:51]
	v_mfma_f32_16x16x32_bf16 v[44:47], v[170:173], v[220:223], v[44:47]
	v_mfma_f32_16x16x32_bf16 v[40:43], v[178:181], v[220:223], v[40:43]
	v_mfma_f32_16x16x32_bf16 v[36:39], v[170:173], v[228:231], v[36:39]
	v_mfma_f32_16x16x32_bf16 v[32:35], v[178:181], v[228:231], v[32:35]
	s_setprio 0
	s_setprio 1
	v_mfma_f32_16x16x32_bf16 v[28:31], v[184:187], v[200:203], v[28:31]
	v_mfma_f32_16x16x32_bf16 v[24:27], v[192:195], v[200:203], v[24:27]
	v_mfma_f32_16x16x32_bf16 v[20:23], v[184:187], v[208:211], v[20:23]
	v_mfma_f32_16x16x32_bf16 v[16:19], v[192:195], v[208:211], v[16:19]
	v_mfma_f32_16x16x32_bf16 v[12:15], v[184:187], v[216:219], v[12:15]
	v_mfma_f32_16x16x32_bf16 v[8:11], v[192:195], v[216:219], v[8:11]
	v_mfma_f32_16x16x32_bf16 v[4:7], v[184:187], v[224:227], v[4:7]
	v_mfma_f32_16x16x32_bf16 v[0:3], v[192:195], v[224:227], v[0:3]
	v_mfma_f32_16x16x32_bf16 v[28:31], v[188:191], v[204:207], v[28:31]
	v_mfma_f32_16x16x32_bf16 v[24:27], v[196:199], v[204:207], v[24:27]
	v_mfma_f32_16x16x32_bf16 v[20:23], v[188:191], v[212:215], v[20:23]
	v_mfma_f32_16x16x32_bf16 v[16:19], v[196:199], v[212:215], v[16:19]
	v_mfma_f32_16x16x32_bf16 v[12:15], v[188:191], v[220:223], v[12:15]
	v_mfma_f32_16x16x32_bf16 v[8:11], v[196:199], v[220:223], v[8:11]
	v_mfma_f32_16x16x32_bf16 v[4:7], v[188:191], v[228:231], v[4:7]
	v_mfma_f32_16x16x32_bf16 v[0:3], v[196:199], v[228:231], v[0:3]
	s_setprio 0
	s_barrier
	s_add_i32 s59, 0, 0x18000
	v_add_u32_e32 v136, s59, v160
	s_add_i32 s60, 0, 0x1c000
	ds_read_b128 v[148:151], v136
	ds_read_b128 v[170:173], v136 offset:1024
	ds_read_b128 v[174:177], v136 offset:2048
	ds_read_b128 v[178:181], v136 offset:3072
	v_add_u32_e32 v136, s60, v160
	ds_read_b128 v[184:187], v136
	ds_read_b128 v[188:191], v136 offset:1024
	ds_read_b128 v[192:195], v136 offset:2048
	ds_read_b128 v[196:199], v136 offset:3072
	s_add_u32 s36, s36, 0x80000
	s_addc_u32 s37, s37, 0
	s_mov_b32 m0, s43
	v_lshl_add_u64 v[238:239], s[36:37], 0, v[128:129]
	ds_read_b128 v[200:203], v164 offset:32768
	ds_read_b128 v[204:207], v164 offset:33792
	ds_read_b128 v[208:211], v164 offset:34816
	ds_read_b128 v[212:215], v164 offset:35840
	ds_read_b128 v[216:219], v164 offset:36864
	ds_read_b128 v[220:223], v164 offset:37888
	ds_read_b128 v[224:227], v164 offset:38912
	ds_read_b128 v[228:231], v164 offset:39936
	global_load_lds_dwordx4 v[238:239], off
	v_lshl_add_u64 v[238:239], s[36:37], 0, v[132:133]
	s_mov_b32 m0, s44
	s_nop 0
	global_load_lds_dwordx4 v[238:239], off
	s_waitcnt vmcnt(8)
	s_waitcnt lgkmcnt(0)
	s_barrier
	s_setprio 1
	s_waitcnt lgkmcnt(0)
	v_mfma_f32_16x16x32_bf16 v[124:127], v[148:151], v[200:203], v[124:127]
	v_mfma_f32_16x16x32_bf16 v[120:123], v[174:177], v[200:203], v[120:123]
	v_mfma_f32_16x16x32_bf16 v[116:119], v[148:151], v[208:211], v[116:119]
	v_mfma_f32_16x16x32_bf16 v[112:115], v[174:177], v[208:211], v[112:115]
	v_mfma_f32_16x16x32_bf16 v[108:111], v[148:151], v[216:219], v[108:111]
	v_mfma_f32_16x16x32_bf16 v[104:107], v[174:177], v[216:219], v[104:107]
	v_mfma_f32_16x16x32_bf16 v[100:103], v[148:151], v[224:227], v[100:103]
	v_mfma_f32_16x16x32_bf16 v[96:99], v[174:177], v[224:227], v[96:99]
	v_mfma_f32_16x16x32_bf16 v[124:127], v[170:173], v[204:207], v[124:127]
	v_mfma_f32_16x16x32_bf16 v[120:123], v[178:181], v[204:207], v[120:123]
	v_mfma_f32_16x16x32_bf16 v[116:119], v[170:173], v[212:215], v[116:119]
	v_mfma_f32_16x16x32_bf16 v[112:115], v[178:181], v[212:215], v[112:115]
	v_mfma_f32_16x16x32_bf16 v[108:111], v[170:173], v[220:223], v[108:111]
	v_mfma_f32_16x16x32_bf16 v[104:107], v[178:181], v[220:223], v[104:107]
	v_mfma_f32_16x16x32_bf16 v[100:103], v[170:173], v[228:231], v[100:103]
	v_mfma_f32_16x16x32_bf16 v[96:99], v[178:181], v[228:231], v[96:99]
	s_setprio 0
	s_setprio 1
	v_mfma_f32_16x16x32_bf16 v[92:95], v[184:187], v[200:203], v[92:95]
	v_mfma_f32_16x16x32_bf16 v[88:91], v[192:195], v[200:203], v[88:91]
	v_mfma_f32_16x16x32_bf16 v[84:87], v[184:187], v[208:211], v[84:87]
	v_mfma_f32_16x16x32_bf16 v[80:83], v[192:195], v[208:211], v[80:83]
	v_mfma_f32_16x16x32_bf16 v[76:79], v[184:187], v[216:219], v[76:79]
	v_mfma_f32_16x16x32_bf16 v[72:75], v[192:195], v[216:219], v[72:75]
	v_mfma_f32_16x16x32_bf16 v[68:71], v[184:187], v[224:227], v[68:71]
	v_mfma_f32_16x16x32_bf16 v[64:67], v[192:195], v[224:227], v[64:67]
	v_mfma_f32_16x16x32_bf16 v[92:95], v[188:191], v[204:207], v[92:95]
	v_mfma_f32_16x16x32_bf16 v[88:91], v[196:199], v[204:207], v[88:91]
	v_mfma_f32_16x16x32_bf16 v[84:87], v[188:191], v[212:215], v[84:87]
	v_mfma_f32_16x16x32_bf16 v[80:83], v[196:199], v[212:215], v[80:83]
	v_mfma_f32_16x16x32_bf16 v[76:79], v[188:191], v[220:223], v[76:79]
	v_mfma_f32_16x16x32_bf16 v[72:75], v[196:199], v[220:223], v[72:75]
	v_mfma_f32_16x16x32_bf16 v[68:71], v[188:191], v[228:231], v[68:71]
	v_mfma_f32_16x16x32_bf16 v[64:67], v[196:199], v[228:231], v[64:67]
	s_setprio 0
	s_barrier
; #define PG8_STAGE(bufoff, gbase, voff) do { _Pragma("unroll") for (int _i = 0; _i < 2; ++_i) \
;         __builtin_amdgcn_global_load_lds((const unsigned*)((const char*)(gbase) + (voff)[_i]), (PG8_LAS unsigned*)(lds + (bufoff) + ldsw + _i * 8192), 16, 0, 0); } while (0)
; #define PG8_LDA(dst, b, h) do { _Pragma("unroll") for (int m = 0; m < 4; ++m) _Pragma("unroll") for (int k = 0; k < 2; ++k) dst[m][k] = *(const PG8_LAS bf16x8*)(lds + PG8_SA(b, h) + aoff + m * 2048 + k * 1024); } while (0)
; #define PG8_LDB(dst, b, h) do { _Pragma("unroll") for (int n = 0; n < 2; ++n) _Pragma("unroll") for (int k = 0; k < 2; ++k) dst[n][k] = *(const PG8_LAS bf16x8*)(lds + PG8_SB(b, h) + boff + n * 2048 + k * 1024); } while (0)
; template <class Epi, class Sched, bool ALIGN_EPI = false, bool SP2 = false>
; __device__ __forceinline__ void gemm_phase(PG8_LAS unsigned char* lds, const Gemm g, const Sched& S, const Epi& E) {
;     ...
;         for (int t = 0; t < nt; t += 2) {
;             const bool last = (t == nt - 2);
;             const char* a1 = cA + (size_t)(t + 1) * kstep;
;             const char* a2 = last ? nA : cA + (size_t)(t + 2) * kstep; const char* b2 = last ? nB : cB + (size_t)(t + 2) * kstep;
;             const char* a3 = a2 + kstep; const char* b3 = b2 + kstep;
;             if (last && has_next) S.a_ready(nxt);
;             if constexpr (SP2) {
;             PG8_LDB(B0, 0, 0); PG8_LDB(B1, 0, 1); PG8_SCHED; PG8_LDA(At, 0, 0); PG8_STAGE(PG8_SA(1, 1), a1 + hstep, voffA);
;             PG8_WAIT_V(8); PG8_WAIT_L(0); PG8_BAR; PG8_MMA(0, 0, At, B0); PG8_MMA(0, 1, At, B1); PG8_BAR; PG8_SCHED;
;             PG8_LDA(At, 0, 1); PG8_STAGE(PG8_SB(0, 0), b2, voffB); PG8_STAGE(PG8_SB(0, 1), b2 + hstep, voffB); PG8_STAGE(PG8_SA(0, 0), a2, voffA);
;             PG8_WAIT_V(8); PG8_WAIT_L(0); PG8_BAR; PG8_MMA(1, 0, At, B0); PG8_MMA(1, 1, At, B1); PG8_BAR; PG8_SCHED;
;             PG8_LDB(B0, 1, 0); PG8_LDB(B1, 1, 1); PG8_SCHED; PG8_LDA(At, 1, 0); PG8_STAGE(PG8_SA(0, 1), a2 + hstep, voffA);
;             PG8_WAIT_V(8); PG8_WAIT_L(0); PG8_BAR; PG8_MMA(0, 0, At, B0); PG8_MMA(0, 1, At, B1); PG8_BAR; PG8_SCHED;
;             PG8_LDA(At, 1, 1); PG8_STAGE(PG8_SB(1, 0), b3, voffB); PG8_STAGE(PG8_SB(1, 1), b3 + hstep, voffB); PG8_STAGE(PG8_SA(1, 0), a3, voffA);
;             PG8_WAIT_V(8); PG8_WAIT_L(0); PG8_BAR; PG8_MMA(1, 0, At, B0); PG8_MMA(1, 1, At, B1); PG8_BAR; PG8_SCHED;
	s_add_i32 s36, s59, s33
	v_lshl_add_u64 v[152:153], v[152:153], 0, s[14:15]
	s_mov_b32 m0, s36
	ds_read_b128 v[200:203], v164 offset:49152
	ds_read_b128 v[204:207], v164 offset:50176
	ds_read_b128 v[208:211], v164 offset:51200
	ds_read_b128 v[212:215], v164 offset:52224
	ds_read_b128 v[216:219], v164 offset:53248
	ds_read_b128 v[220:223], v164 offset:54272
	ds_read_b128 v[224:227], v164 offset:55296
	ds_read_b128 v[228:231], v164 offset:56320
	global_load_lds_dwordx4 v[152:153], off
	s_add_i32 m0, s36, 0x2000
	s_add_u32 s34, s34, 0x80080
	v_lshl_add_u64 v[152:153], v[232:233], 0, s[14:15]
	s_addc_u32 s35, s35, 0
	s_add_i32 s36, s60, s33
	global_load_lds_dwordx4 v[152:153], off
	v_lshl_add_u64 v[152:153], s[34:35], 0, v[130:131]
	s_mov_b32 m0, s36
	s_nop 0
	global_load_lds_dwordx4 v[152:153], off
	v_lshl_add_u64 v[152:153], s[34:35], 0, v[134:135]
	s_add_i32 m0, s36, 0x2000
	s_nop 0
	global_load_lds_dwordx4 v[152:153], off
	v_lshl_add_u64 v[152:153], v[234:235], 0, s[14:15]
	s_mov_b32 m0, s46
	s_nop 0
	global_load_lds_dwordx4 v[152:153], off
	v_lshl_add_u64 v[152:153], v[236:237], 0, s[14:15]
	s_mov_b32 m0, s47
	s_nop 0
	global_load_lds_dwordx4 v[152:153], off
	s_waitcnt vmcnt(8)
	s_waitcnt lgkmcnt(0)
	s_barrier
	s_setprio 1
	s_waitcnt lgkmcnt(0)
	v_mfma_f32_16x16x32_bf16 v[60:63], v[148:151], v[200:203], v[60:63]
	v_mfma_f32_16x16x32_bf16 v[56:59], v[174:177], v[200:203], v[56:59]
	v_mfma_f32_16x16x32_bf16 v[52:55], v[148:151], v[208:211], v[52:55]
	v_mfma_f32_16x16x32_bf16 v[48:51], v[174:177], v[208:211], v[48:51]
	v_mfma_f32_16x16x32_bf16 v[44:47], v[148:151], v[216:219], v[44:47]
	v_mfma_f32_16x16x32_bf16 v[40:43], v[174:177], v[216:219], v[40:43]
	v_mfma_f32_16x16x32_bf16 v[36:39], v[148:151], v[224:227], v[36:39]
	v_mfma_f32_16x16x32_bf16 v[32:35], v[174:177], v[224:227], v[32:35]
	v_mfma_f32_16x16x32_bf16 v[60:63], v[170:173], v[204:207], v[60:63]
	v_mfma_f32_16x16x32_bf16 v[56:59], v[178:181], v[204:207], v[56:59]
	v_mfma_f32_16x16x32_bf16 v[52:55], v[170:173], v[212:215], v[52:55]
	v_mfma_f32_16x16x32_bf16 v[48:51], v[178:181], v[212:215], v[48:51]
	v_mfma_f32_16x16x32_bf16 v[44:47], v[170:173], v[220:223], v[44:47]
	v_mfma_f32_16x16x32_bf16 v[40:43], v[178:181], v[220:223], v[40:43]
	v_mfma_f32_16x16x32_bf16 v[36:39], v[170:173], v[228:231], v[36:39]
	v_mfma_f32_16x16x32_bf16 v[32:35], v[178:181], v[228:231], v[32:35]
	s_setprio 0
	s_setprio 1
	v_mfma_f32_16x16x32_bf16 v[28:31], v[184:187], v[200:203], v[28:31]
	v_mfma_f32_16x16x32_bf16 v[24:27], v[192:195], v[200:203], v[24:27]
	v_mfma_f32_16x16x32_bf16 v[20:23], v[184:187], v[208:211], v[20:23]
	v_mfma_f32_16x16x32_bf16 v[16:19], v[192:195], v[208:211], v[16:19]
	v_mfma_f32_16x16x32_bf16 v[12:15], v[184:187], v[216:219], v[12:15]
	v_mfma_f32_16x16x32_bf16 v[8:11], v[192:195], v[216:219], v[8:11]
	v_mfma_f32_16x16x32_bf16 v[4:7], v[184:187], v[224:227], v[4:7]
	v_mfma_f32_16x16x32_bf16 v[0:3], v[192:195], v[224:227], v[0:3]
	v_mfma_f32_16x16x32_bf16 v[28:31], v[188:191], v[204:207], v[28:31]
	v_mfma_f32_16x16x32_bf16 v[24:27], v[196:199], v[204:207], v[24:27]
	v_mfma_f32_16x16x32_bf16 v[20:23], v[188:191], v[212:215], v[20:23]
	v_mfma_f32_16x16x32_bf16 v[16:19], v[196:199], v[212:215], v[16:19]
	v_mfma_f32_16x16x32_bf16 v[12:15], v[188:191], v[220:223], v[12:15]
	v_mfma_f32_16x16x32_bf16 v[8:11], v[196:199], v[220:223], v[8:11]
	v_mfma_f32_16x16x32_bf16 v[4:7], v[188:191], v[228:231], v[4:7]
	v_mfma_f32_16x16x32_bf16 v[0:3], v[196:199], v[228:231], v[0:3]
	s_add_i32 s58, s58, 2
	s_add_u32 s30, s30, 0x100
	s_addc_u32 s31, s31, 0
	s_add_u32 s56, s56, 0x100
	s_addc_u32 s57, s57, 0
	s_cmp_gt_u32 s58, 29
	s_setprio 0
	s_barrier
	s_cbranch_scc0 .LBB0_1071
	s_and_b64 vcc, exec, s[16:17]
	s_cbranch_vccz .LBB0_1074
	s_barrier

; #define PG8_STAGE(bufoff, gbase, voff) do { _Pragma("unroll") for (int _i = 0; _i < 2; ++_i) \
;         __builtin_amdgcn_global_load_lds((const unsigned*)((const char*)(gbase) + (voff)[_i]), (PG8_LAS unsigned*)(lds + (bufoff) + ldsw + _i * 8192), 16, 0, 0); } while (0)
; #define PG8_LDA(dst, b, h) do { _Pragma("unroll") for (int m = 0; m < 4; ++m) _Pragma("unroll") for (int k = 0; k < 2; ++k) dst[m][k] = *(const PG8_LAS bf16x8*)(lds + PG8_SA(b, h) + aoff + m * 2048 + k * 1024); } while (0)
; #define PG8_LDB(dst, b, h) do { _Pragma("unroll") for (int n = 0; n < 2; ++n) _Pragma("unroll") for (int k = 0; k < 2; ++k) dst[n][k] = *(const PG8_LAS bf16x8*)(lds + PG8_SB(b, h) + boff + n * 2048 + k * 1024); } while (0)
; #define PG8_MMA(ai, bj, At, Bt) do { __builtin_amdgcn_s_setprio(1); _Pragma("unroll") for (int m = 0; m < 4; ++m) _Pragma("unroll") for (int n = 0; n < 2; ++n) _Pragma("unroll") for (int k = 0; k < 2; ++k) \
;         acc[ai][bj][m][n] = __builtin_amdgcn_mfma_f32_16x16x32_bf16(Bt[n][k], At[m][k], acc[ai][bj][m][n], 0, 0, 0); __builtin_amdgcn_s_setprio(0); } while (0)
; #define PG8_WAIT_V(n) asm volatile("s_waitcnt vmcnt(" #n ")" ::: "memory")
; #define PG8_BAR __builtin_amdgcn_s_barrier()
; template <class Epi, class Sched, bool ALIGN_EPI = false, bool SP2 = false>
; __device__ __forceinline__ void gemm_phase(PG8_LAS unsigned char* lds, const Gemm g, const Sched& S, const Epi& E) {
;     ...
;         for (int t = 0; t < nt; t += 2) {
;             const bool last = (t == nt - 2);
;             const char* a1 = cA + (size_t)(t + 1) * kstep;
;             const char* a2 = last ? nA : cA + (size_t)(t + 2) * kstep; const char* b2 = last ? nB : cB + (size_t)(t + 2) * kstep;
;             const char* a3 = a2 + kstep; const char* b3 = b2 + kstep;
;             if (last && has_next) S.a_ready(nxt);
;             if constexpr (SP2) {
;             PG8_LDB(B0, 0, 0); PG8_LDB(B1, 0, 1); PG8_SCHED; PG8_LDA(At, 0, 0); PG8_STAGE(PG8_SA(1, 1), a1 + hstep, voffA);
;             PG8_WAIT_V(8); PG8_WAIT_L(0); PG8_BAR; PG8_MMA(0, 0, At, B0); PG8_MMA(0, 1, At, B1); PG8_BAR; PG8_SCHED;
;             PG8_LDA(At, 0, 1); PG8_STAGE(PG8_SB(0, 0), b2, voffB); PG8_STAGE(PG8_SB(0, 1), b2 + hstep, voffB); PG8_STAGE(PG8_SA(0, 0), a2, voffA);
;             PG8_WAIT_V(8); PG8_WAIT_L(0); PG8_BAR; PG8_MMA(1, 0, At, B0); PG8_MMA(1, 1, At, B1); PG8_BAR; PG8_SCHED;
.LBB0_1343:
	v_add_u32_e32 v134, s46, v161
	ds_read_b128 v[144:147], v134
	ds_read_b128 v[166:169], v134 offset:1024
	ds_read_b128 v[170:173], v134 offset:2048
	ds_read_b128 v[174:177], v134 offset:3072
	v_add_u32_e32 v134, s47, v161
	ds_read_b128 v[178:181], v134
	ds_read_b128 v[184:187], v134 offset:1024
	ds_read_b128 v[188:191], v134 offset:2048
	ds_read_b128 v[192:195], v134 offset:3072
	s_add_u32 s34, s30, 0xfff00080
	s_addc_u32 s35, s31, -1
	s_cmp_eq_u32 s56, 60
	s_cselect_b32 s37, s21, s35
	s_cselect_b32 s36, s27, s34
	s_cselect_b32 s35, s19, s55
	s_cselect_b32 s34, s49, s54
	v_lshl_add_u64 v[148:149], s[30:31], 0, v[136:137]
	s_add_i32 m0, s29, 0xc000
	ds_read_b128 v[196:199], v163
	ds_read_b128 v[200:203], v163 offset:1024
	ds_read_b128 v[204:207], v163 offset:2048
	ds_read_b128 v[208:211], v163 offset:3072
	ds_read_b128 v[212:215], v163 offset:4096
	ds_read_b128 v[216:219], v163 offset:5120
	ds_read_b128 v[220:223], v163 offset:6144
	ds_read_b128 v[224:227], v163 offset:7168
	global_load_lds_dwordx4 v[148:149], off
	v_lshl_add_u64 v[148:149], s[30:31], 0, v[138:139]
	s_add_i32 m0, s29, 0xe000
	s_nop 0
	global_load_lds_dwordx4 v[148:149], off
	s_waitcnt vmcnt(8)
	s_waitcnt lgkmcnt(0)
	s_barrier
	s_setprio 1
	s_waitcnt lgkmcnt(0)
	v_mfma_f32_16x16x32_bf16 v[120:123], v[144:147], v[196:199], v[120:123]
	v_mfma_f32_16x16x32_bf16 v[124:127], v[170:173], v[196:199], v[124:127]
	v_mfma_f32_16x16x32_bf16 v[112:115], v[144:147], v[204:207], v[112:115]
	v_mfma_f32_16x16x32_bf16 v[116:119], v[170:173], v[204:207], v[116:119]
	v_mfma_f32_16x16x32_bf16 v[104:107], v[144:147], v[212:215], v[104:107]
	v_mfma_f32_16x16x32_bf16 v[108:111], v[170:173], v[212:215], v[108:111]
	v_mfma_f32_16x16x32_bf16 v[96:99], v[144:147], v[220:223], v[96:99]
	v_mfma_f32_16x16x32_bf16 v[100:103], v[170:173], v[220:223], v[100:103]
	v_mfma_f32_16x16x32_bf16 v[120:123], v[166:169], v[200:203], v[120:123]
	v_mfma_f32_16x16x32_bf16 v[124:127], v[174:177], v[200:203], v[124:127]
	v_mfma_f32_16x16x32_bf16 v[112:115], v[166:169], v[208:211], v[112:115]
	v_mfma_f32_16x16x32_bf16 v[116:119], v[174:177], v[208:211], v[116:119]
	v_mfma_f32_16x16x32_bf16 v[104:107], v[166:169], v[216:219], v[104:107]
	v_mfma_f32_16x16x32_bf16 v[108:111], v[174:177], v[216:219], v[108:111]
	v_mfma_f32_16x16x32_bf16 v[96:99], v[166:169], v[224:227], v[96:99]
	v_mfma_f32_16x16x32_bf16 v[100:103], v[174:177], v[224:227], v[100:103]
	s_setprio 0
	s_setprio 1
	v_mfma_f32_16x16x32_bf16 v[76:79], v[178:181], v[196:199], v[76:79]
	v_mfma_f32_16x16x32_bf16 v[92:95], v[188:191], v[196:199], v[92:95]
	v_mfma_f32_16x16x32_bf16 v[72:75], v[178:181], v[204:207], v[72:75]
	v_mfma_f32_16x16x32_bf16 v[88:91], v[188:191], v[204:207], v[88:91]
	v_mfma_f32_16x16x32_bf16 v[68:71], v[178:181], v[212:215], v[68:71]
	v_mfma_f32_16x16x32_bf16 v[84:87], v[188:191], v[212:215], v[84:87]
	v_mfma_f32_16x16x32_bf16 v[64:67], v[178:181], v[220:223], v[64:67]
	v_mfma_f32_16x16x32_bf16 v[80:83], v[188:191], v[220:223], v[80:83]
	v_mfma_f32_16x16x32_bf16 v[76:79], v[184:187], v[200:203], v[76:79]
	v_mfma_f32_16x16x32_bf16 v[92:95], v[192:195], v[200:203], v[92:95]
	v_mfma_f32_16x16x32_bf16 v[72:75], v[184:187], v[208:211], v[72:75]
	v_mfma_f32_16x16x32_bf16 v[88:91], v[192:195], v[208:211], v[88:91]
	v_mfma_f32_16x16x32_bf16 v[68:71], v[184:187], v[216:219], v[68:71]
	v_mfma_f32_16x16x32_bf16 v[84:87], v[192:195], v[216:219], v[84:87]
	v_mfma_f32_16x16x32_bf16 v[64:67], v[184:187], v[224:227], v[64:67]
	v_mfma_f32_16x16x32_bf16 v[80:83], v[192:195], v[224:227], v[80:83]
	s_setprio 0
	s_barrier
	s_add_i32 s57, s46, s33
	v_lshl_add_u64 v[148:149], s[34:35], 0, v[128:129]
	s_mov_b32 m0, s57
	ds_read_b128 v[196:199], v163 offset:16384
	ds_read_b128 v[200:203], v163 offset:17408
	ds_read_b128 v[204:207], v163 offset:18432
	ds_read_b128 v[208:211], v163 offset:19456
	ds_read_b128 v[212:215], v163 offset:20480
	ds_read_b128 v[216:219], v163 offset:21504
	ds_read_b128 v[220:223], v163 offset:22528
	ds_read_b128 v[224:227], v163 offset:23552
	global_load_lds_dwordx4 v[148:149], off
	s_add_i32 m0, s57, 0x2000
	s_add_u32 s58, s34, 0x100000
	v_lshl_add_u64 v[228:229], s[34:35], 0, v[130:131]
	s_addc_u32 s59, s35, 0
	s_add_i32 s57, s47, s33
	global_load_lds_dwordx4 v[228:229], off
	v_lshl_add_u64 v[230:231], s[58:59], 0, v[128:129]
	s_mov_b32 m0, s57
	v_lshl_add_u64 v[232:233], s[36:37], 0, v[130:131]
	global_load_lds_dwordx4 v[230:231], off
	v_lshl_add_u64 v[230:231], s[58:59], 0, v[130:131]
	s_add_i32 m0, s57, 0x2000
	s_nop 0
	global_load_lds_dwordx4 v[230:231], off
	v_lshl_add_u64 v[230:231], s[36:37], 0, v[128:129]
	s_mov_b32 m0, s29
	s_nop 0
	global_load_lds_dwordx4 v[230:231], off
	s_mov_b32 m0, s38
	s_nop 0
	global_load_lds_dwordx4 v[232:233], off
	s_waitcnt vmcnt(8)
	s_waitcnt lgkmcnt(0)
	s_barrier
; #define PG8_STAGE(bufoff, gbase, voff) do { _Pragma("unroll") for (int _i = 0; _i < 2; ++_i) \
;         __builtin_amdgcn_global_load_lds((const unsigned*)((const char*)(gbase) + (voff)[_i]), (PG8_LAS unsigned*)(lds + (bufoff) + ldsw + _i * 8192), 16, 0, 0); } while (0)
; #define PG8_LDA(dst, b, h) do { _Pragma("unroll") for (int m = 0; m < 4; ++m) _Pragma("unroll") for (int k = 0; k < 2; ++k) dst[m][k] = *(const PG8_LAS bf16x8*)(lds + PG8_SA(b, h) + aoff + m * 2048 + k * 1024); } while (0)
; #define PG8_LDB(dst, b, h) do { _Pragma("unroll") for (int n = 0; n < 2; ++n) _Pragma("unroll") for (int k = 0; k < 2; ++k) dst[n][k] = *(const PG8_LAS bf16x8*)(lds + PG8_SB(b, h) + boff + n * 2048 + k * 1024); } while (0)
; #define PG8_MMA(ai, bj, At, Bt) do { __builtin_amdgcn_s_setprio(1); _Pragma("unroll") for (int m = 0; m < 4; ++m) _Pragma("unroll") for (int n = 0; n < 2; ++n) _Pragma("unroll") for (int k = 0; k < 2; ++k) \
;         acc[ai][bj][m][n] = __builtin_amdgcn_mfma_f32_16x16x32_bf16(Bt[n][k], At[m][k], acc[ai][bj][m][n], 0, 0, 0); __builtin_amdgcn_s_setprio(0); } while (0)
; #define PG8_WAIT_V(n) asm volatile("s_waitcnt vmcnt(" #n ")" ::: "memory")
; #define PG8_WAIT_L(n) asm volatile("s_waitcnt lgkmcnt(" #n ")" ::: "memory")
; #define PG8_BAR __builtin_amdgcn_s_barrier()
; #define PG8_SCHED __builtin_amdgcn_sched_barrier(0)
; template <class Epi, class Sched, bool ALIGN_EPI = false, bool SP2 = false>
; __device__ __forceinline__ void gemm_phase(PG8_LAS unsigned char* lds, const Gemm g, const Sched& S, const Epi& E) {
;     ...
;             PG8_WAIT_V(8); PG8_WAIT_L(0); PG8_BAR; PG8_MMA(1, 0, At, B0); PG8_MMA(1, 1, At, B1); PG8_BAR; PG8_SCHED;
;             PG8_LDB(B0, 1, 0); PG8_LDB(B1, 1, 1); PG8_SCHED; PG8_LDA(At, 1, 0); PG8_STAGE(PG8_SA(0, 1), a2 + hstep, voffA);
;             PG8_WAIT_V(8); PG8_WAIT_L(0); PG8_BAR; PG8_MMA(0, 0, At, B0); PG8_MMA(0, 1, At, B1); PG8_BAR; PG8_SCHED;
	s_setprio 1
	s_waitcnt lgkmcnt(0)
	v_mfma_f32_16x16x32_bf16 v[56:59], v[144:147], v[196:199], v[56:59]
	v_mfma_f32_16x16x32_bf16 v[60:63], v[170:173], v[196:199], v[60:63]
	v_mfma_f32_16x16x32_bf16 v[48:51], v[144:147], v[204:207], v[48:51]
	v_mfma_f32_16x16x32_bf16 v[52:55], v[170:173], v[204:207], v[52:55]
	v_mfma_f32_16x16x32_bf16 v[40:43], v[144:147], v[212:215], v[40:43]
	v_mfma_f32_16x16x32_bf16 v[44:47], v[170:173], v[212:215], v[44:47]
	v_mfma_f32_16x16x32_bf16 v[32:35], v[144:147], v[220:223], v[32:35]
	v_mfma_f32_16x16x32_bf16 v[36:39], v[170:173], v[220:223], v[36:39]
	v_mfma_f32_16x16x32_bf16 v[56:59], v[166:169], v[200:203], v[56:59]
	v_mfma_f32_16x16x32_bf16 v[60:63], v[174:177], v[200:203], v[60:63]
	v_mfma_f32_16x16x32_bf16 v[48:51], v[166:169], v[208:211], v[48:51]
	v_mfma_f32_16x16x32_bf16 v[52:55], v[174:177], v[208:211], v[52:55]
	v_mfma_f32_16x16x32_bf16 v[40:43], v[166:169], v[216:219], v[40:43]
	v_mfma_f32_16x16x32_bf16 v[44:47], v[174:177], v[216:219], v[44:47]
	v_mfma_f32_16x16x32_bf16 v[32:35], v[166:169], v[224:227], v[32:35]
	v_mfma_f32_16x16x32_bf16 v[36:39], v[174:177], v[224:227], v[36:39]
	s_setprio 0
	s_setprio 1
	v_mfma_f32_16x16x32_bf16 v[12:15], v[178:181], v[196:199], v[12:15]
	v_mfma_f32_16x16x32_bf16 v[28:31], v[188:191], v[196:199], v[28:31]
	v_mfma_f32_16x16x32_bf16 v[8:11], v[178:181], v[204:207], v[8:11]
	v_mfma_f32_16x16x32_bf16 v[24:27], v[188:191], v[204:207], v[24:27]
	v_mfma_f32_16x16x32_bf16 v[4:7], v[178:181], v[212:215], v[4:7]
	v_mfma_f32_16x16x32_bf16 v[20:23], v[188:191], v[212:215], v[20:23]
	v_mfma_f32_16x16x32_bf16 v[0:3], v[178:181], v[220:223], v[0:3]
	v_mfma_f32_16x16x32_bf16 v[16:19], v[188:191], v[220:223], v[16:19]
	v_mfma_f32_16x16x32_bf16 v[12:15], v[184:187], v[200:203], v[12:15]
	v_mfma_f32_16x16x32_bf16 v[28:31], v[192:195], v[200:203], v[28:31]
	v_mfma_f32_16x16x32_bf16 v[8:11], v[184:187], v[208:211], v[8:11]
	v_mfma_f32_16x16x32_bf16 v[24:27], v[192:195], v[208:211], v[24:27]
	v_mfma_f32_16x16x32_bf16 v[4:7], v[184:187], v[216:219], v[4:7]
	v_mfma_f32_16x16x32_bf16 v[20:23], v[192:195], v[216:219], v[20:23]
	v_mfma_f32_16x16x32_bf16 v[0:3], v[184:187], v[224:227], v[0:3]
	v_mfma_f32_16x16x32_bf16 v[16:19], v[192:195], v[224:227], v[16:19]
	s_setprio 0
	s_barrier
	s_add_i32 s57, 0, 0x18000
	v_add_u32_e32 v134, s57, v161
	s_add_i32 s58, 0, 0x1c000
	ds_read_b128 v[144:147], v134
	ds_read_b128 v[166:169], v134 offset:1024
	ds_read_b128 v[170:173], v134 offset:2048
	ds_read_b128 v[174:177], v134 offset:3072
	v_add_u32_e32 v134, s58, v161
	ds_read_b128 v[178:181], v134
	ds_read_b128 v[184:187], v134 offset:1024
	ds_read_b128 v[188:191], v134 offset:2048
	ds_read_b128 v[192:195], v134 offset:3072
	s_add_u32 s36, s36, 0x100000
	s_addc_u32 s37, s37, 0
	s_mov_b32 m0, s39
	v_lshl_add_u64 v[234:235], s[36:37], 0, v[128:129]
	ds_read_b128 v[196:199], v163 offset:32768
	ds_read_b128 v[200:203], v163 offset:33792
	ds_read_b128 v[204:207], v163 offset:34816
	ds_read_b128 v[208:211], v163 offset:35840
	ds_read_b128 v[212:215], v163 offset:36864
	ds_read_b128 v[216:219], v163 offset:37888
	ds_read_b128 v[220:223], v163 offset:38912
	ds_read_b128 v[224:227], v163 offset:39936
	global_load_lds_dwordx4 v[234:235], off
	v_lshl_add_u64 v[234:235], s[36:37], 0, v[130:131]
	s_mov_b32 m0, s40
	s_nop 0
	global_load_lds_dwordx4 v[234:235], off
	s_waitcnt vmcnt(8)
	s_waitcnt lgkmcnt(0)
	s_barrier
	s_setprio 1
	s_waitcnt lgkmcnt(0)
	v_mfma_f32_16x16x32_bf16 v[120:123], v[144:147], v[196:199], v[120:123]
	v_mfma_f32_16x16x32_bf16 v[124:127], v[170:173], v[196:199], v[124:127]
	v_mfma_f32_16x16x32_bf16 v[112:115], v[144:147], v[204:207], v[112:115]
	v_mfma_f32_16x16x32_bf16 v[116:119], v[170:173], v[204:207], v[116:119]
	v_mfma_f32_16x16x32_bf16 v[104:107], v[144:147], v[212:215], v[104:107]
	v_mfma_f32_16x16x32_bf16 v[108:111], v[170:173], v[212:215], v[108:111]
	v_mfma_f32_16x16x32_bf16 v[96:99], v[144:147], v[220:223], v[96:99]
	v_mfma_f32_16x16x32_bf16 v[100:103], v[170:173], v[220:223], v[100:103]
	v_mfma_f32_16x16x32_bf16 v[120:123], v[166:169], v[200:203], v[120:123]
	v_mfma_f32_16x16x32_bf16 v[124:127], v[174:177], v[200:203], v[124:127]
	v_mfma_f32_16x16x32_bf16 v[112:115], v[166:169], v[208:211], v[112:115]
	v_mfma_f32_16x16x32_bf16 v[116:119], v[174:177], v[208:211], v[116:119]
	v_mfma_f32_16x16x32_bf16 v[104:107], v[166:169], v[216:219], v[104:107]
	v_mfma_f32_16x16x32_bf16 v[108:111], v[174:177], v[216:219], v[108:111]
	v_mfma_f32_16x16x32_bf16 v[96:99], v[166:169], v[224:227], v[96:99]
	v_mfma_f32_16x16x32_bf16 v[100:103], v[174:177], v[224:227], v[100:103]
	s_setprio 0
	s_setprio 1
	v_mfma_f32_16x16x32_bf16 v[76:79], v[178:181], v[196:199], v[76:79]
	v_mfma_f32_16x16x32_bf16 v[92:95], v[188:191], v[196:199], v[92:95]
	v_mfma_f32_16x16x32_bf16 v[72:75], v[178:181], v[204:207], v[72:75]
	v_mfma_f32_16x16x32_bf16 v[88:91], v[188:191], v[204:207], v[88:91]
	v_mfma_f32_16x16x32_bf16 v[68:71], v[178:181], v[212:215], v[68:71]
	v_mfma_f32_16x16x32_bf16 v[84:87], v[188:191], v[212:215], v[84:87]
	v_mfma_f32_16x16x32_bf16 v[64:67], v[178:181], v[220:223], v[64:67]
	v_mfma_f32_16x16x32_bf16 v[80:83], v[188:191], v[220:223], v[80:83]
	v_mfma_f32_16x16x32_bf16 v[76:79], v[184:187], v[200:203], v[76:79]
	v_mfma_f32_16x16x32_bf16 v[92:95], v[192:195], v[200:203], v[92:95]
	v_mfma_f32_16x16x32_bf16 v[72:75], v[184:187], v[208:211], v[72:75]
	v_mfma_f32_16x16x32_bf16 v[88:91], v[192:195], v[208:211], v[88:91]
	v_mfma_f32_16x16x32_bf16 v[68:71], v[184:187], v[216:219], v[68:71]
	v_mfma_f32_16x16x32_bf16 v[84:87], v[192:195], v[216:219], v[84:87]
	v_mfma_f32_16x16x32_bf16 v[64:67], v[184:187], v[224:227], v[64:67]
	v_mfma_f32_16x16x32_bf16 v[80:83], v[192:195], v[224:227], v[80:83]
	s_setprio 0
	s_barrier
; #define PG8_STAGE(bufoff, gbase, voff) do { _Pragma("unroll") for (int _i = 0; _i < 2; ++_i) \
;         __builtin_amdgcn_global_load_lds((const unsigned*)((const char*)(gbase) + (voff)[_i]), (PG8_LAS unsigned*)(lds + (bufoff) + ldsw + _i * 8192), 16, 0, 0); } while (0)
; #define PG8_LDA(dst, b, h) do { _Pragma("unroll") for (int m = 0; m < 4; ++m) _Pragma("unroll") for (int k = 0; k < 2; ++k) dst[m][k] = *(const PG8_LAS bf16x8*)(lds + PG8_SA(b, h) + aoff + m * 2048 + k * 1024); } while (0)
; #define PG8_LDB(dst, b, h) do { _Pragma("unroll") for (int n = 0; n < 2; ++n) _Pragma("unroll") for (int k = 0; k < 2; ++k) dst[n][k] = *(const PG8_LAS bf16x8*)(lds + PG8_SB(b, h) + boff + n * 2048 + k * 1024); } while (0)
; template <class Epi, class Sched, bool ALIGN_EPI = false, bool SP2 = false>
; __device__ __forceinline__ void gemm_phase(PG8_LAS unsigned char* lds, const Gemm g, const Sched& S, const Epi& E) {
;     ...
;         for (int t = 0; t < nt; t += 2) {
;             const bool last = (t == nt - 2);
;             const char* a1 = cA + (size_t)(t + 1) * kstep;
;             const char* a2 = last ? nA : cA + (size_t)(t + 2) * kstep; const char* b2 = last ? nB : cB + (size_t)(t + 2) * kstep;
;             const char* a3 = a2 + kstep; const char* b3 = b2 + kstep;
;             if (last && has_next) S.a_ready(nxt);
;             if constexpr (SP2) {
;             PG8_LDB(B0, 0, 0); PG8_LDB(B1, 0, 1); PG8_SCHED; PG8_LDA(At, 0, 0); PG8_STAGE(PG8_SA(1, 1), a1 + hstep, voffA);
;             PG8_WAIT_V(8); PG8_WAIT_L(0); PG8_BAR; PG8_MMA(0, 0, At, B0); PG8_MMA(0, 1, At, B1); PG8_BAR; PG8_SCHED;
;             PG8_LDA(At, 0, 1); PG8_STAGE(PG8_SB(0, 0), b2, voffB); PG8_STAGE(PG8_SB(0, 1), b2 + hstep, voffB); PG8_STAGE(PG8_SA(0, 0), a2, voffA);
;             PG8_WAIT_V(8); PG8_WAIT_L(0); PG8_BAR; PG8_MMA(1, 0, At, B0); PG8_MMA(1, 1, At, B1); PG8_BAR; PG8_SCHED;
;             PG8_LDB(B0, 1, 0); PG8_LDB(B1, 1, 1); PG8_SCHED; PG8_LDA(At, 1, 0); PG8_STAGE(PG8_SA(0, 1), a2 + hstep, voffA);
;             PG8_WAIT_V(8); PG8_WAIT_L(0); PG8_BAR; PG8_MMA(0, 0, At, B0); PG8_MMA(0, 1, At, B1); PG8_BAR; PG8_SCHED;
;             PG8_LDA(At, 1, 1); PG8_STAGE(PG8_SB(1, 0), b3, voffB); PG8_STAGE(PG8_SB(1, 1), b3 + hstep, voffB); PG8_STAGE(PG8_SA(1, 0), a3, voffA);
;             PG8_WAIT_V(8); PG8_WAIT_L(0); PG8_BAR; PG8_MMA(1, 0, At, B0); PG8_MMA(1, 1, At, B1); PG8_BAR; PG8_SCHED;
	s_add_i32 s36, s57, s33
	v_lshl_add_u64 v[148:149], v[148:149], 0, s[14:15]
	s_mov_b32 m0, s36
	ds_read_b128 v[196:199], v163 offset:49152
	ds_read_b128 v[200:203], v163 offset:50176
	ds_read_b128 v[204:207], v163 offset:51200
	ds_read_b128 v[208:211], v163 offset:52224
	ds_read_b128 v[212:215], v163 offset:53248
	ds_read_b128 v[216:219], v163 offset:54272
	ds_read_b128 v[220:223], v163 offset:55296
	ds_read_b128 v[224:227], v163 offset:56320
	global_load_lds_dwordx4 v[148:149], off
	s_add_i32 m0, s36, 0x2000
	s_add_u32 s34, s34, 0x100080
	v_lshl_add_u64 v[148:149], v[228:229], 0, s[14:15]
	s_addc_u32 s35, s35, 0
	s_add_i32 s36, s58, s33
	global_load_lds_dwordx4 v[148:149], off
	v_lshl_add_u64 v[148:149], s[34:35], 0, v[128:129]
	s_mov_b32 m0, s36
	s_nop 0
	global_load_lds_dwordx4 v[148:149], off
	v_lshl_add_u64 v[148:149], s[34:35], 0, v[130:131]
	s_add_i32 m0, s36, 0x2000
	s_nop 0
	global_load_lds_dwordx4 v[148:149], off
	v_lshl_add_u64 v[148:149], v[230:231], 0, s[14:15]
	s_mov_b32 m0, s41
	s_nop 0
	global_load_lds_dwordx4 v[148:149], off
	v_lshl_add_u64 v[148:149], v[232:233], 0, s[14:15]
	s_mov_b32 m0, s42
	s_nop 0
	global_load_lds_dwordx4 v[148:149], off
	s_waitcnt vmcnt(8)
	s_waitcnt lgkmcnt(0)
	s_barrier
	s_setprio 1
	s_waitcnt lgkmcnt(0)
	v_mfma_f32_16x16x32_bf16 v[56:59], v[144:147], v[196:199], v[56:59]
	v_mfma_f32_16x16x32_bf16 v[60:63], v[170:173], v[196:199], v[60:63]
	v_mfma_f32_16x16x32_bf16 v[48:51], v[144:147], v[204:207], v[48:51]
	v_mfma_f32_16x16x32_bf16 v[52:55], v[170:173], v[204:207], v[52:55]
	v_mfma_f32_16x16x32_bf16 v[40:43], v[144:147], v[212:215], v[40:43]
	v_mfma_f32_16x16x32_bf16 v[44:47], v[170:173], v[212:215], v[44:47]
	v_mfma_f32_16x16x32_bf16 v[32:35], v[144:147], v[220:223], v[32:35]
	v_mfma_f32_16x16x32_bf16 v[36:39], v[170:173], v[220:223], v[36:39]
	v_mfma_f32_16x16x32_bf16 v[56:59], v[166:169], v[200:203], v[56:59]
	v_mfma_f32_16x16x32_bf16 v[60:63], v[174:177], v[200:203], v[60:63]
	v_mfma_f32_16x16x32_bf16 v[48:51], v[166:169], v[208:211], v[48:51]
	v_mfma_f32_16x16x32_bf16 v[52:55], v[174:177], v[208:211], v[52:55]
	v_mfma_f32_16x16x32_bf16 v[40:43], v[166:169], v[216:219], v[40:43]
	v_mfma_f32_16x16x32_bf16 v[44:47], v[174:177], v[216:219], v[44:47]
	v_mfma_f32_16x16x32_bf16 v[32:35], v[166:169], v[224:227], v[32:35]
	v_mfma_f32_16x16x32_bf16 v[36:39], v[174:177], v[224:227], v[36:39]
	s_setprio 0
	s_setprio 1
	v_mfma_f32_16x16x32_bf16 v[12:15], v[178:181], v[196:199], v[12:15]
	v_mfma_f32_16x16x32_bf16 v[28:31], v[188:191], v[196:199], v[28:31]
	v_mfma_f32_16x16x32_bf16 v[8:11], v[178:181], v[204:207], v[8:11]
	v_mfma_f32_16x16x32_bf16 v[24:27], v[188:191], v[204:207], v[24:27]
	v_mfma_f32_16x16x32_bf16 v[4:7], v[178:181], v[212:215], v[4:7]
	v_mfma_f32_16x16x32_bf16 v[20:23], v[188:191], v[212:215], v[20:23]
	v_mfma_f32_16x16x32_bf16 v[0:3], v[178:181], v[220:223], v[0:3]
	v_mfma_f32_16x16x32_bf16 v[16:19], v[188:191], v[220:223], v[16:19]
	v_mfma_f32_16x16x32_bf16 v[12:15], v[184:187], v[200:203], v[12:15]
	v_mfma_f32_16x16x32_bf16 v[28:31], v[192:195], v[200:203], v[28:31]
	v_mfma_f32_16x16x32_bf16 v[8:11], v[184:187], v[208:211], v[8:11]
	v_mfma_f32_16x16x32_bf16 v[24:27], v[192:195], v[208:211], v[24:27]
	v_mfma_f32_16x16x32_bf16 v[4:7], v[184:187], v[216:219], v[4:7]
	v_mfma_f32_16x16x32_bf16 v[20:23], v[192:195], v[216:219], v[20:23]
	v_mfma_f32_16x16x32_bf16 v[0:3], v[184:187], v[224:227], v[0:3]
	v_mfma_f32_16x16x32_bf16 v[16:19], v[192:195], v[224:227], v[16:19]
	s_add_i32 s56, s56, 2
	s_add_u32 s30, s30, 0x100
	s_addc_u32 s31, s31, 0
	s_add_u32 s54, s54, 0x100
	s_addc_u32 s55, s55, 0
	s_cmp_gt_u32 s56, 61
	s_setprio 0
	s_barrier
	s_cbranch_scc0 .LBB0_1343
	s_and_b64 vcc, exec, s[16:17]
	s_cbranch_vccz .LBB0_1346
	s_barrier
